# kv up-projection tiles re-dealt between workgroups (1 vs 3) to balance the 1.5-round q up-projection; row-interleaved scale+store in the hand-written epilogues
# speedup vs baseline: 1.0156x; 1.0156x over previous
.LBB0_271:
	s_lshl_b32 s0, s29, 8
	s_add_i32 s0, s0, s82
	v_and_or_b32 v0, v193, 15, s0
	v_bfe_u32 v218, v193, 4, 2
	s_lshl_b32 s0, s28, 3
	s_or_b32 s0, s0, s81
	s_mul_i32 s2, s0, 43
	s_lshr_b32 s2, s2, 7
	s_mul_i32 s2, s2, 3
	s_sub_i32 s0, s0, s2
	s_lshl_b32 s2, s28, 9
	s_lshl_b32 s24, s83, 1
	s_or_b32 s2, s2, s24
	v_lshl_or_b32 v219, v218, 4, s2
	v_mad_u32_u24 v219, v0, s47, v219
	s_mov_b32 vcc_lo, -1
	s_mov_b32 vcc_hi, 0xffff
	s_cmp_eq_u32 s0, 2
	s_cbranch_scc1 .Luq_r0
	s_cmp_eq_u32 s0, 1
	s_cbranch_scc1 .Luq_r1
	v_add_f32_e32 v194, v195, v194
	v_add_f32_e32 v196, v196, v197
	v_add_f32_e32 v198, v199, v198
	v_add_f32_e32 v200, v200, v201
	v_add_f32_e32 v202, v203, v202
	v_add_f32_e32 v204, v204, v205
	v_add_f32_e32 v206, v207, v206
	v_add_f32_e32 v208, v208, v209
	v_add_f32_e32 v194, v194, v196
	v_add_f32_e32 v198, v198, v200
	v_add_f32_e32 v202, v202, v204
	v_add_f32_e32 v206, v206, v208
	v_cndmask_b32_e32 v221, 0, v221, vcc
	v_cndmask_b32_e32 v222, 0, v222, vcc
	v_cndmask_b32_e32 v223, 0, v223, vcc
	v_cndmask_b32_e32 v224, 0, v224, vcc
	v_cndmask_b32_e32 v194, 0, v194, vcc
	v_cndmask_b32_e32 v198, 0, v198, vcc
	v_cndmask_b32_e32 v202, 0, v202, vcc
	v_cndmask_b32_e32 v206, 0, v206, vcc
	ds_swizzle_b32 v195, v221 offset:swizzle(SWAP,16)
	ds_swizzle_b32 v196, v222 offset:swizzle(SWAP,16)
	ds_swizzle_b32 v199, v223 offset:swizzle(SWAP,16)
	ds_swizzle_b32 v200, v224 offset:swizzle(SWAP,16)
	ds_swizzle_b32 v203, v194 offset:swizzle(SWAP,16)
	ds_swizzle_b32 v204, v198 offset:swizzle(SWAP,16)
	ds_swizzle_b32 v207, v202 offset:swizzle(SWAP,16)
	ds_swizzle_b32 v208, v206 offset:swizzle(SWAP,16)
	s_waitcnt lgkmcnt(0)
	v_add_f32_e32 v221, v221, v195
	v_add_f32_e32 v222, v222, v196
	v_add_f32_e32 v223, v223, v199
	v_add_f32_e32 v224, v224, v200
	v_add_f32_e32 v194, v194, v203
	v_add_f32_e32 v198, v198, v204
	v_add_f32_e32 v202, v202, v207
	v_add_f32_e32 v206, v206, v208
	v_mov_b32_e32 v197, v221
	v_mov_b32_e32 v201, v222
	v_mov_b32_e32 v205, v223
	v_mov_b32_e32 v209, v224
	v_mov_b32_e32 v240, v194
	v_mov_b32_e32 v241, v198
	v_mov_b32_e32 v242, v202
	v_mov_b32_e32 v243, v206
	v_permlane32_swap_b32_e32 v221, v197
	v_permlane32_swap_b32_e32 v222, v201
	v_permlane32_swap_b32_e32 v223, v205
	v_permlane32_swap_b32_e32 v224, v209
	v_permlane32_swap_b32_e32 v194, v240
	v_permlane32_swap_b32_e32 v198, v241
	v_permlane32_swap_b32_e32 v202, v242
	v_permlane32_swap_b32_e32 v206, v243
	v_add_f32_e32 v221, v221, v197
	v_add_f32_e32 v222, v222, v201
	v_add_f32_e32 v223, v223, v205
	v_add_f32_e32 v224, v224, v209
	v_add_f32_e32 v194, v194, v240
	v_add_f32_e32 v198, v198, v241
	v_add_f32_e32 v202, v202, v242
	v_add_f32_e32 v206, v206, v243
	v_fmamk_f32 v221, v221, 0x3b2aaaab, v192
	v_fmamk_f32 v222, v222, 0x3b2aaaab, v192
	v_fmamk_f32 v223, v223, 0x3b2aaaab, v192
	v_fmamk_f32 v224, v224, 0x3b2aaaab, v192
	v_fmamk_f32 v194, v194, 0x3b2aaaab, v192
	v_fmamk_f32 v198, v198, 0x3b2aaaab, v192
	v_fmamk_f32 v202, v202, 0x3b2aaaab, v192
	v_fmamk_f32 v206, v206, 0x3b2aaaab, v192
	v_rsq_f32_e32 v221, v221
	v_rsq_f32_e32 v222, v222
	v_rsq_f32_e32 v223, v223
	v_rsq_f32_e32 v224, v224
	v_rsq_f32_e32 v194, v194
	v_rsq_f32_e32 v198, v198
	v_rsq_f32_e32 v202, v202
	v_rsq_f32_e32 v206, v206
	v_mul_f32_e32 v221, 0x3e16c740, v221
	v_mul_f32_e32 v222, 0x3e16c740, v222
	v_mul_f32_e32 v223, 0x3e16c740, v223
	v_mul_f32_e32 v224, 0x3e16c740, v224
	v_mul_f32_e32 v194, 0x3e16c740, v194
	v_mul_f32_e32 v198, 0x3e16c740, v198
	v_mul_f32_e32 v202, 0x3e16c740, v202
	v_mul_f32_e32 v206, 0x3e16c740, v206
	v_pk_mul_f32 v[134:135], v[134:135], v[220:221] op_sel:[0,1] op_sel_hi:[1,1]
	v_pk_mul_f32 v[136:137], v[136:137], v[220:221] op_sel:[0,1] op_sel_hi:[1,1]
	v_pk_mul_f32 v[130:131], v[130:131], v[220:221] op_sel:[0,1] op_sel_hi:[1,1]
	v_pk_mul_f32 v[132:133], v[132:133], v[220:221] op_sel:[0,1] op_sel_hi:[1,1]
	v_pk_mul_f32 v[126:127], v[126:127], v[220:221] op_sel:[0,1] op_sel_hi:[1,1]
	v_pk_mul_f32 v[128:129], v[128:129], v[220:221] op_sel:[0,1] op_sel_hi:[1,1]
	v_pk_mul_f32 v[122:123], v[122:123], v[220:221] op_sel:[0,1] op_sel_hi:[1,1]
	v_pk_mul_f32 v[124:125], v[124:125], v[220:221] op_sel:[0,1] op_sel_hi:[1,1]
	v_cvt_pk_bf16_f32 v134, v134, v135
	v_cvt_pk_bf16_f32 v135, v136, v137
	v_cvt_pk_bf16_f32 v136, v130, v131
	v_cvt_pk_bf16_f32 v137, v132, v133
	v_add_u32_e32 v246, 0x0, v219
	global_store_dwordx4 v246, v[134:137], s[8:9]
	v_cvt_pk_bf16_f32 v126, v126, v127
	v_cvt_pk_bf16_f32 v127, v128, v129
	v_cvt_pk_bf16_f32 v128, v122, v123
	v_cvt_pk_bf16_f32 v129, v124, v125
	v_add_u32_e32 v247, 0x0, v219
	global_store_dwordx4 v247, v[126:129], s[8:9] offset:256
	v_pk_mul_f32 v[118:119], v[118:119], v[222:223] op_sel_hi:[1,0]
	v_pk_mul_f32 v[120:121], v[120:121], v[222:223] op_sel_hi:[1,0]
	v_pk_mul_f32 v[114:115], v[114:115], v[222:223] op_sel_hi:[1,0]
	v_pk_mul_f32 v[116:117], v[116:117], v[222:223] op_sel_hi:[1,0]
	v_pk_mul_f32 v[110:111], v[110:111], v[222:223] op_sel_hi:[1,0]
	v_pk_mul_f32 v[112:113], v[112:113], v[222:223] op_sel_hi:[1,0]
	v_pk_mul_f32 v[106:107], v[106:107], v[222:223] op_sel_hi:[1,0]
	v_pk_mul_f32 v[108:109], v[108:109], v[222:223] op_sel_hi:[1,0]
	v_cvt_pk_bf16_f32 v118, v118, v119
	v_cvt_pk_bf16_f32 v119, v120, v121
	v_cvt_pk_bf16_f32 v120, v114, v115
	v_cvt_pk_bf16_f32 v121, v116, v117
	v_add_u32_e32 v246, 0xc000, v219
	global_store_dwordx4 v246, v[118:121], s[8:9]
	v_cvt_pk_bf16_f32 v110, v110, v111
	v_cvt_pk_bf16_f32 v111, v112, v113
	v_cvt_pk_bf16_f32 v112, v106, v107
	v_cvt_pk_bf16_f32 v113, v108, v109
	v_add_u32_e32 v247, 0xc000, v219
	global_store_dwordx4 v247, v[110:113], s[8:9] offset:256
	v_pk_mul_f32 v[102:103], v[102:103], v[222:223] op_sel:[0,1] op_sel_hi:[1,1]
	v_pk_mul_f32 v[104:105], v[104:105], v[222:223] op_sel:[0,1] op_sel_hi:[1,1]
	v_pk_mul_f32 v[98:99], v[98:99], v[222:223] op_sel:[0,1] op_sel_hi:[1,1]
	v_pk_mul_f32 v[100:101], v[100:101], v[222:223] op_sel:[0,1] op_sel_hi:[1,1]
	v_pk_mul_f32 v[94:95], v[94:95], v[222:223] op_sel:[0,1] op_sel_hi:[1,1]
	v_pk_mul_f32 v[96:97], v[96:97], v[222:223] op_sel:[0,1] op_sel_hi:[1,1]
	v_pk_mul_f32 v[90:91], v[90:91], v[222:223] op_sel:[0,1] op_sel_hi:[1,1]
	v_pk_mul_f32 v[92:93], v[92:93], v[222:223] op_sel:[0,1] op_sel_hi:[1,1]
	v_cvt_pk_bf16_f32 v102, v102, v103
	v_cvt_pk_bf16_f32 v103, v104, v105
	v_cvt_pk_bf16_f32 v104, v98, v99
	v_cvt_pk_bf16_f32 v105, v100, v101
	v_add_u32_e32 v246, 0x18000, v219
	global_store_dwordx4 v246, v[102:105], s[8:9]
	v_cvt_pk_bf16_f32 v94, v94, v95
	v_cvt_pk_bf16_f32 v95, v96, v97
	v_cvt_pk_bf16_f32 v96, v90, v91
	v_cvt_pk_bf16_f32 v97, v92, v93
	v_add_u32_e32 v247, 0x18000, v219
	global_store_dwordx4 v247, v[94:97], s[8:9] offset:256
	v_pk_mul_f32 v[86:87], v[86:87], v[224:225] op_sel_hi:[1,0]
	v_pk_mul_f32 v[88:89], v[88:89], v[224:225] op_sel_hi:[1,0]
	v_pk_mul_f32 v[82:83], v[82:83], v[224:225] op_sel_hi:[1,0]
	v_pk_mul_f32 v[84:85], v[84:85], v[224:225] op_sel_hi:[1,0]
	v_pk_mul_f32 v[78:79], v[78:79], v[224:225] op_sel_hi:[1,0]
	v_pk_mul_f32 v[80:81], v[80:81], v[224:225] op_sel_hi:[1,0]
	v_pk_mul_f32 v[74:75], v[74:75], v[224:225] op_sel_hi:[1,0]
	v_pk_mul_f32 v[76:77], v[76:77], v[224:225] op_sel_hi:[1,0]
	v_cvt_pk_bf16_f32 v86, v86, v87
	v_cvt_pk_bf16_f32 v87, v88, v89
	v_cvt_pk_bf16_f32 v88, v82, v83
	v_cvt_pk_bf16_f32 v89, v84, v85
	v_add_u32_e32 v246, 0x24000, v219
	global_store_dwordx4 v246, v[86:89], s[8:9]
	v_cvt_pk_bf16_f32 v78, v78, v79
	v_cvt_pk_bf16_f32 v79, v80, v81
	v_cvt_pk_bf16_f32 v80, v74, v75
	v_cvt_pk_bf16_f32 v81, v76, v77
	v_add_u32_e32 v247, 0x24000, v219
	global_store_dwordx4 v247, v[78:81], s[8:9] offset:256
	v_pk_mul_f32 v[70:71], v[70:71], v[194:195] op_sel_hi:[1,0]
	v_pk_mul_f32 v[72:73], v[72:73], v[194:195] op_sel_hi:[1,0]
	v_pk_mul_f32 v[66:67], v[66:67], v[194:195] op_sel_hi:[1,0]
	v_pk_mul_f32 v[68:69], v[68:69], v[194:195] op_sel_hi:[1,0]
	v_pk_mul_f32 v[62:63], v[62:63], v[194:195] op_sel_hi:[1,0]
	v_pk_mul_f32 v[64:65], v[64:65], v[194:195] op_sel_hi:[1,0]
	v_pk_mul_f32 v[58:59], v[58:59], v[194:195] op_sel_hi:[1,0]
	v_pk_mul_f32 v[60:61], v[60:61], v[194:195] op_sel_hi:[1,0]
	v_cvt_pk_bf16_f32 v70, v70, v71
	v_cvt_pk_bf16_f32 v71, v72, v73
	v_cvt_pk_bf16_f32 v72, v66, v67
	v_cvt_pk_bf16_f32 v73, v68, v69
	v_add_u32_e32 v246, 0x60000, v219
	global_store_dwordx4 v246, v[70:73], s[8:9]
	v_cvt_pk_bf16_f32 v62, v62, v63
	v_cvt_pk_bf16_f32 v63, v64, v65
	v_cvt_pk_bf16_f32 v64, v58, v59
	v_cvt_pk_bf16_f32 v65, v60, v61
	v_add_u32_e32 v247, 0x60000, v219
	global_store_dwordx4 v247, v[62:65], s[8:9] offset:256
	v_pk_mul_f32 v[46:47], v[46:47], v[198:199] op_sel_hi:[1,0]
	v_pk_mul_f32 v[48:49], v[48:49], v[198:199] op_sel_hi:[1,0]
	v_pk_mul_f32 v[42:43], v[42:43], v[198:199] op_sel_hi:[1,0]
	v_pk_mul_f32 v[44:45], v[44:45], v[198:199] op_sel_hi:[1,0]
	v_pk_mul_f32 v[38:39], v[38:39], v[198:199] op_sel_hi:[1,0]
	v_pk_mul_f32 v[40:41], v[40:41], v[198:199] op_sel_hi:[1,0]
	v_pk_mul_f32 v[34:35], v[34:35], v[198:199] op_sel_hi:[1,0]
	v_pk_mul_f32 v[36:37], v[36:37], v[198:199] op_sel_hi:[1,0]
	v_cvt_pk_bf16_f32 v46, v46, v47
	v_cvt_pk_bf16_f32 v47, v48, v49
	v_cvt_pk_bf16_f32 v48, v42, v43
	v_cvt_pk_bf16_f32 v49, v44, v45
	v_add_u32_e32 v246, 0x6c000, v219
	global_store_dwordx4 v246, v[46:49], s[8:9]
	v_cvt_pk_bf16_f32 v38, v38, v39
	v_cvt_pk_bf16_f32 v39, v40, v41
	v_cvt_pk_bf16_f32 v40, v34, v35
	v_cvt_pk_bf16_f32 v41, v36, v37
	v_add_u32_e32 v247, 0x6c000, v219
	global_store_dwordx4 v247, v[38:41], s[8:9] offset:256
	v_pk_mul_f32 v[30:31], v[30:31], v[202:203] op_sel_hi:[1,0]
	v_pk_mul_f32 v[32:33], v[32:33], v[202:203] op_sel_hi:[1,0]
	v_pk_mul_f32 v[26:27], v[26:27], v[202:203] op_sel_hi:[1,0]
	v_pk_mul_f32 v[28:29], v[28:29], v[202:203] op_sel_hi:[1,0]
	v_pk_mul_f32 v[22:23], v[22:23], v[202:203] op_sel_hi:[1,0]
	v_pk_mul_f32 v[24:25], v[24:25], v[202:203] op_sel_hi:[1,0]
	v_pk_mul_f32 v[18:19], v[18:19], v[202:203] op_sel_hi:[1,0]
	v_pk_mul_f32 v[20:21], v[20:21], v[202:203] op_sel_hi:[1,0]
	v_cvt_pk_bf16_f32 v30, v30, v31
	v_cvt_pk_bf16_f32 v31, v32, v33
	v_cvt_pk_bf16_f32 v32, v26, v27
	v_cvt_pk_bf16_f32 v33, v28, v29
	v_add_u32_e32 v246, 0x78000, v219
	global_store_dwordx4 v246, v[30:33], s[8:9]
	v_cvt_pk_bf16_f32 v22, v22, v23
	v_cvt_pk_bf16_f32 v23, v24, v25
	v_cvt_pk_bf16_f32 v24, v18, v19
	v_cvt_pk_bf16_f32 v25, v20, v21
	v_add_u32_e32 v247, 0x78000, v219
	global_store_dwordx4 v247, v[22:25], s[8:9] offset:256
	v_pk_mul_f32 v[14:15], v[14:15], v[206:207] op_sel_hi:[1,0]
	v_pk_mul_f32 v[16:17], v[16:17], v[206:207] op_sel_hi:[1,0]
	v_pk_mul_f32 v[10:11], v[10:11], v[206:207] op_sel_hi:[1,0]
	v_pk_mul_f32 v[12:13], v[12:13], v[206:207] op_sel_hi:[1,0]
	v_pk_mul_f32 v[6:7], v[6:7], v[206:207] op_sel_hi:[1,0]
	v_pk_mul_f32 v[8:9], v[8:9], v[206:207] op_sel_hi:[1,0]
	v_pk_mul_f32 v[2:3], v[2:3], v[206:207] op_sel_hi:[1,0]
	v_pk_mul_f32 v[4:5], v[4:5], v[206:207] op_sel_hi:[1,0]
	v_cvt_pk_bf16_f32 v14, v14, v15
	v_cvt_pk_bf16_f32 v15, v16, v17
	v_cvt_pk_bf16_f32 v16, v10, v11
	v_cvt_pk_bf16_f32 v17, v12, v13
	v_add_u32_e32 v246, 0x84000, v219
	global_store_dwordx4 v246, v[14:17], s[8:9]
	v_cvt_pk_bf16_f32 v6, v6, v7
	v_cvt_pk_bf16_f32 v7, v8, v9
	v_cvt_pk_bf16_f32 v8, v2, v3
	v_cvt_pk_bf16_f32 v9, v4, v5
	v_add_u32_e32 v247, 0x84000, v219
	global_store_dwordx4 v247, v[6:9], s[8:9] offset:256
	s_branch .Luq_end
.Luq_r0:
	v_and_b32_e32 v246, 1, v218
	v_and_b32_e32 v247, 2, v218
	v_lshlrev_b32_e32 v244, 6, v0
	v_lshl_add_u32 v244, v246, 5, v244
	v_lshl_add_u32 v244, v247, 3, v244
	v_add_u32_e32 v245, 0x2000, v244
	global_load_dwordx4 v[228:231], v244, s[10:11]
	global_load_dwordx4 v[232:235], v244, s[12:13]
	global_load_dwordx4 v[236:239], v244, s[10:11] offset:1024
	global_load_dwordx4 v[50:53], v244, s[12:13] offset:1024
	global_load_dwordx4 v[54:57], v244, s[10:11] offset:2048
	global_load_dwordx4 v[184:187], v244, s[12:13] offset:2048
	global_load_dwordx4 v[188:191], v244, s[10:11] offset:3072
	global_load_dwordx4 v[214:217], v244, s[12:13] offset:3072
	global_load_dwordx4 v[150:153], v245, s[10:11]
	global_load_dwordx4 v[154:157], v245, s[12:13]
	global_load_dwordx4 v[158:161], v245, s[10:11] offset:1024
	global_load_dwordx4 v[162:165], v245, s[12:13] offset:1024
	global_load_dwordx4 v[166:169], v245, s[10:11] offset:2048
	global_load_dwordx4 v[170:173], v245, s[12:13] offset:2048
	global_load_dwordx4 v[174:177], v245, s[10:11] offset:3072
	global_load_dwordx4 v[180:183], v245, s[12:13] offset:3072
	v_add_f32_e32 v194, v195, v194
	v_add_f32_e32 v196, v196, v197
	v_add_f32_e32 v198, v199, v198
	v_add_f32_e32 v200, v200, v201
	v_add_f32_e32 v202, v203, v202
	v_add_f32_e32 v204, v204, v205
	v_add_f32_e32 v206, v207, v206
	v_add_f32_e32 v208, v208, v209
	v_add_f32_e32 v194, v194, v196
	v_add_f32_e32 v198, v198, v200
	v_add_f32_e32 v202, v202, v204
	v_add_f32_e32 v206, v206, v208
	v_cndmask_b32_e32 v221, 0, v221, vcc
	v_cndmask_b32_e32 v222, 0, v222, vcc
	v_cndmask_b32_e32 v223, 0, v223, vcc
	v_cndmask_b32_e32 v224, 0, v224, vcc
	v_cndmask_b32_e32 v194, 0, v194, vcc
	v_cndmask_b32_e32 v198, 0, v198, vcc
	v_cndmask_b32_e32 v202, 0, v202, vcc
	v_cndmask_b32_e32 v206, 0, v206, vcc
	ds_swizzle_b32 v195, v221 offset:swizzle(SWAP,16)
	ds_swizzle_b32 v196, v222 offset:swizzle(SWAP,16)
	ds_swizzle_b32 v199, v223 offset:swizzle(SWAP,16)
	ds_swizzle_b32 v200, v224 offset:swizzle(SWAP,16)
	ds_swizzle_b32 v203, v194 offset:swizzle(SWAP,16)
	ds_swizzle_b32 v204, v198 offset:swizzle(SWAP,16)
	ds_swizzle_b32 v207, v202 offset:swizzle(SWAP,16)
	ds_swizzle_b32 v208, v206 offset:swizzle(SWAP,16)
	s_waitcnt lgkmcnt(0)
	v_add_f32_e32 v221, v221, v195
	v_add_f32_e32 v222, v222, v196
	v_add_f32_e32 v223, v223, v199
	v_add_f32_e32 v224, v224, v200
	v_add_f32_e32 v194, v194, v203
	v_add_f32_e32 v198, v198, v204
	v_add_f32_e32 v202, v202, v207
	v_add_f32_e32 v206, v206, v208
	v_mov_b32_e32 v197, v221
	v_mov_b32_e32 v201, v222
	v_mov_b32_e32 v205, v223
	v_mov_b32_e32 v209, v224
	v_mov_b32_e32 v240, v194
	v_mov_b32_e32 v241, v198
	v_mov_b32_e32 v242, v202
	v_mov_b32_e32 v243, v206
	v_permlane32_swap_b32_e32 v221, v197
	v_permlane32_swap_b32_e32 v222, v201
	v_permlane32_swap_b32_e32 v223, v205
	v_permlane32_swap_b32_e32 v224, v209
	v_permlane32_swap_b32_e32 v194, v240
	v_permlane32_swap_b32_e32 v198, v241
	v_permlane32_swap_b32_e32 v202, v242
	v_permlane32_swap_b32_e32 v206, v243
	v_add_f32_e32 v221, v221, v197
	v_add_f32_e32 v222, v222, v201
	v_add_f32_e32 v223, v223, v205
	v_add_f32_e32 v224, v224, v209
	v_add_f32_e32 v194, v194, v240
	v_add_f32_e32 v198, v198, v241
	v_add_f32_e32 v202, v202, v242
	v_add_f32_e32 v206, v206, v243
	v_fmamk_f32 v221, v221, 0x3b2aaaab, v192
	v_fmamk_f32 v222, v222, 0x3b2aaaab, v192
	v_fmamk_f32 v223, v223, 0x3b2aaaab, v192
	v_fmamk_f32 v224, v224, 0x3b2aaaab, v192
	v_fmamk_f32 v194, v194, 0x3b2aaaab, v192
	v_fmamk_f32 v198, v198, 0x3b2aaaab, v192
	v_fmamk_f32 v202, v202, 0x3b2aaaab, v192
	v_fmamk_f32 v206, v206, 0x3b2aaaab, v192
	v_rsq_f32_e32 v221, v221
	v_rsq_f32_e32 v222, v222
	v_rsq_f32_e32 v223, v223
	v_rsq_f32_e32 v224, v224
	v_rsq_f32_e32 v194, v194
	v_rsq_f32_e32 v198, v198
	v_rsq_f32_e32 v202, v202
	v_rsq_f32_e32 v206, v206
	v_mul_f32_e32 v221, 0x3e16c740, v221
	v_mul_f32_e32 v222, 0x3e16c740, v222
	v_mul_f32_e32 v223, 0x3e16c740, v223
	v_mul_f32_e32 v224, 0x3e16c740, v224
	v_mul_f32_e32 v194, 0x3e16c740, v194
	v_mul_f32_e32 v198, 0x3e16c740, v198
	v_mul_f32_e32 v202, 0x3e16c740, v202
	v_mul_f32_e32 v206, 0x3e16c740, v206
	v_pk_mul_f32 v[134:135], v[134:135], v[220:221] op_sel:[0,1] op_sel_hi:[1,1]
	v_pk_mul_f32 v[136:137], v[136:137], v[220:221] op_sel:[0,1] op_sel_hi:[1,1]
	v_pk_mul_f32 v[130:131], v[130:131], v[220:221] op_sel:[0,1] op_sel_hi:[1,1]
	v_pk_mul_f32 v[132:133], v[132:133], v[220:221] op_sel:[0,1] op_sel_hi:[1,1]
	v_pk_mul_f32 v[126:127], v[126:127], v[220:221] op_sel:[0,1] op_sel_hi:[1,1]
	v_pk_mul_f32 v[128:129], v[128:129], v[220:221] op_sel:[0,1] op_sel_hi:[1,1]
	v_pk_mul_f32 v[122:123], v[122:123], v[220:221] op_sel:[0,1] op_sel_hi:[1,1]
	v_pk_mul_f32 v[124:125], v[124:125], v[220:221] op_sel:[0,1] op_sel_hi:[1,1]
	v_cvt_pk_bf16_f32 v126, v126, v127
	v_cvt_pk_bf16_f32 v127, v128, v129
	v_cvt_pk_bf16_f32 v128, v122, v123
	v_cvt_pk_bf16_f32 v129, v124, v125
	v_add_u32_e32 v246, 0x0, v219
	global_store_dwordx4 v246, v[126:129], s[8:9] offset:256
	v_pk_mul_f32 v[118:119], v[118:119], v[222:223] op_sel_hi:[1,0]
	v_pk_mul_f32 v[120:121], v[120:121], v[222:223] op_sel_hi:[1,0]
	v_pk_mul_f32 v[114:115], v[114:115], v[222:223] op_sel_hi:[1,0]
	v_pk_mul_f32 v[116:117], v[116:117], v[222:223] op_sel_hi:[1,0]
	v_pk_mul_f32 v[110:111], v[110:111], v[222:223] op_sel_hi:[1,0]
	v_pk_mul_f32 v[112:113], v[112:113], v[222:223] op_sel_hi:[1,0]
	v_pk_mul_f32 v[106:107], v[106:107], v[222:223] op_sel_hi:[1,0]
	v_pk_mul_f32 v[108:109], v[108:109], v[222:223] op_sel_hi:[1,0]
	v_cvt_pk_bf16_f32 v110, v110, v111
	v_cvt_pk_bf16_f32 v111, v112, v113
	v_cvt_pk_bf16_f32 v112, v106, v107
	v_cvt_pk_bf16_f32 v113, v108, v109
	v_add_u32_e32 v247, 0xc000, v219
	global_store_dwordx4 v247, v[110:113], s[8:9] offset:256
	v_pk_mul_f32 v[102:103], v[102:103], v[222:223] op_sel:[0,1] op_sel_hi:[1,1]
	v_pk_mul_f32 v[104:105], v[104:105], v[222:223] op_sel:[0,1] op_sel_hi:[1,1]
	v_pk_mul_f32 v[98:99], v[98:99], v[222:223] op_sel:[0,1] op_sel_hi:[1,1]
	v_pk_mul_f32 v[100:101], v[100:101], v[222:223] op_sel:[0,1] op_sel_hi:[1,1]
	v_pk_mul_f32 v[94:95], v[94:95], v[222:223] op_sel:[0,1] op_sel_hi:[1,1]
	v_pk_mul_f32 v[96:97], v[96:97], v[222:223] op_sel:[0,1] op_sel_hi:[1,1]
	v_pk_mul_f32 v[90:91], v[90:91], v[222:223] op_sel:[0,1] op_sel_hi:[1,1]
	v_pk_mul_f32 v[92:93], v[92:93], v[222:223] op_sel:[0,1] op_sel_hi:[1,1]
	v_cvt_pk_bf16_f32 v94, v94, v95
	v_cvt_pk_bf16_f32 v95, v96, v97
	v_cvt_pk_bf16_f32 v96, v90, v91
	v_cvt_pk_bf16_f32 v97, v92, v93
	v_add_u32_e32 v246, 0x18000, v219
	global_store_dwordx4 v246, v[94:97], s[8:9] offset:256
	v_pk_mul_f32 v[86:87], v[86:87], v[224:225] op_sel_hi:[1,0]
	v_pk_mul_f32 v[88:89], v[88:89], v[224:225] op_sel_hi:[1,0]
	v_pk_mul_f32 v[82:83], v[82:83], v[224:225] op_sel_hi:[1,0]
	v_pk_mul_f32 v[84:85], v[84:85], v[224:225] op_sel_hi:[1,0]
	v_pk_mul_f32 v[78:79], v[78:79], v[224:225] op_sel_hi:[1,0]
	v_pk_mul_f32 v[80:81], v[80:81], v[224:225] op_sel_hi:[1,0]
	v_pk_mul_f32 v[74:75], v[74:75], v[224:225] op_sel_hi:[1,0]
	v_pk_mul_f32 v[76:77], v[76:77], v[224:225] op_sel_hi:[1,0]
	v_cvt_pk_bf16_f32 v78, v78, v79
	v_cvt_pk_bf16_f32 v79, v80, v81
	v_cvt_pk_bf16_f32 v80, v74, v75
	v_cvt_pk_bf16_f32 v81, v76, v77
	v_add_u32_e32 v247, 0x24000, v219
	global_store_dwordx4 v247, v[78:81], s[8:9] offset:256
	v_pk_mul_f32 v[70:71], v[70:71], v[194:195] op_sel_hi:[1,0]
	v_pk_mul_f32 v[72:73], v[72:73], v[194:195] op_sel_hi:[1,0]
	v_pk_mul_f32 v[66:67], v[66:67], v[194:195] op_sel_hi:[1,0]
	v_pk_mul_f32 v[68:69], v[68:69], v[194:195] op_sel_hi:[1,0]
	v_pk_mul_f32 v[62:63], v[62:63], v[194:195] op_sel_hi:[1,0]
	v_pk_mul_f32 v[64:65], v[64:65], v[194:195] op_sel_hi:[1,0]
	v_pk_mul_f32 v[58:59], v[58:59], v[194:195] op_sel_hi:[1,0]
	v_pk_mul_f32 v[60:61], v[60:61], v[194:195] op_sel_hi:[1,0]
	v_cvt_pk_bf16_f32 v62, v62, v63
	v_cvt_pk_bf16_f32 v63, v64, v65
	v_cvt_pk_bf16_f32 v64, v58, v59
	v_cvt_pk_bf16_f32 v65, v60, v61
	v_add_u32_e32 v246, 0x60000, v219
	global_store_dwordx4 v246, v[62:65], s[8:9] offset:256
	v_pk_mul_f32 v[46:47], v[46:47], v[198:199] op_sel_hi:[1,0]
	v_pk_mul_f32 v[48:49], v[48:49], v[198:199] op_sel_hi:[1,0]
	v_pk_mul_f32 v[42:43], v[42:43], v[198:199] op_sel_hi:[1,0]
	v_pk_mul_f32 v[44:45], v[44:45], v[198:199] op_sel_hi:[1,0]
	v_pk_mul_f32 v[38:39], v[38:39], v[198:199] op_sel_hi:[1,0]
	v_pk_mul_f32 v[40:41], v[40:41], v[198:199] op_sel_hi:[1,0]
	v_pk_mul_f32 v[34:35], v[34:35], v[198:199] op_sel_hi:[1,0]
	v_pk_mul_f32 v[36:37], v[36:37], v[198:199] op_sel_hi:[1,0]
	v_cvt_pk_bf16_f32 v38, v38, v39
	v_cvt_pk_bf16_f32 v39, v40, v41
	v_cvt_pk_bf16_f32 v40, v34, v35
	v_cvt_pk_bf16_f32 v41, v36, v37
	v_add_u32_e32 v247, 0x6c000, v219
	global_store_dwordx4 v247, v[38:41], s[8:9] offset:256
	v_pk_mul_f32 v[30:31], v[30:31], v[202:203] op_sel_hi:[1,0]
	v_pk_mul_f32 v[32:33], v[32:33], v[202:203] op_sel_hi:[1,0]
	v_pk_mul_f32 v[26:27], v[26:27], v[202:203] op_sel_hi:[1,0]
	v_pk_mul_f32 v[28:29], v[28:29], v[202:203] op_sel_hi:[1,0]
	v_pk_mul_f32 v[22:23], v[22:23], v[202:203] op_sel_hi:[1,0]
	v_pk_mul_f32 v[24:25], v[24:25], v[202:203] op_sel_hi:[1,0]
	v_pk_mul_f32 v[18:19], v[18:19], v[202:203] op_sel_hi:[1,0]
	v_pk_mul_f32 v[20:21], v[20:21], v[202:203] op_sel_hi:[1,0]
	v_cvt_pk_bf16_f32 v22, v22, v23
	v_cvt_pk_bf16_f32 v23, v24, v25
	v_cvt_pk_bf16_f32 v24, v18, v19
	v_cvt_pk_bf16_f32 v25, v20, v21
	v_add_u32_e32 v246, 0x78000, v219
	global_store_dwordx4 v246, v[22:25], s[8:9] offset:256
	v_pk_mul_f32 v[14:15], v[14:15], v[206:207] op_sel_hi:[1,0]
	v_pk_mul_f32 v[16:17], v[16:17], v[206:207] op_sel_hi:[1,0]
	v_pk_mul_f32 v[10:11], v[10:11], v[206:207] op_sel_hi:[1,0]
	v_pk_mul_f32 v[12:13], v[12:13], v[206:207] op_sel_hi:[1,0]
	v_pk_mul_f32 v[6:7], v[6:7], v[206:207] op_sel_hi:[1,0]
	v_pk_mul_f32 v[8:9], v[8:9], v[206:207] op_sel_hi:[1,0]
	v_pk_mul_f32 v[2:3], v[2:3], v[206:207] op_sel_hi:[1,0]
	v_pk_mul_f32 v[4:5], v[4:5], v[206:207] op_sel_hi:[1,0]
	v_cvt_pk_bf16_f32 v6, v6, v7
	v_cvt_pk_bf16_f32 v7, v8, v9
	v_cvt_pk_bf16_f32 v8, v2, v3
	v_cvt_pk_bf16_f32 v9, v4, v5
	v_add_u32_e32 v247, 0x84000, v219
	global_store_dwordx4 v247, v[6:9], s[8:9] offset:256
	s_waitcnt vmcnt(20)
	v_permlane32_swap_b32_e32 v134, v130
	v_permlane32_swap_b32_e32 v135, v131
	v_permlane32_swap_b32_e32 v136, v132
	v_permlane32_swap_b32_e32 v137, v133
	v_permlane32_swap_b32_e32 v118, v114
	v_permlane32_swap_b32_e32 v119, v115
	v_permlane32_swap_b32_e32 v120, v116
	v_permlane32_swap_b32_e32 v121, v117
	v_pk_mul_f32 v[122:123], v[134:135], v[228:229]
	v_pk_mul_f32 v[124:125], v[136:137], v[230:231]
	v_pk_mul_f32 v[106:107], v[118:119], v[236:237]
	v_pk_mul_f32 v[108:109], v[120:121], v[238:239]
	v_pk_fma_f32 v[122:123], v[130:131], v[232:233], v[122:123] neg_lo:[1,0,0] neg_hi:[1,0,0]
	v_pk_fma_f32 v[124:125], v[132:133], v[234:235], v[124:125] neg_lo:[1,0,0] neg_hi:[1,0,0]
	v_pk_fma_f32 v[106:107], v[114:115], v[50:51], v[106:107] neg_lo:[1,0,0] neg_hi:[1,0,0]
	v_pk_fma_f32 v[108:109], v[116:117], v[52:53], v[108:109] neg_lo:[1,0,0] neg_hi:[1,0,0]
	v_pk_mul_f32 v[130:131], v[130:131], v[228:229]
	v_pk_mul_f32 v[132:133], v[132:133], v[230:231]
	v_pk_mul_f32 v[114:115], v[114:115], v[236:237]
	v_pk_mul_f32 v[116:117], v[116:117], v[238:239]
	v_pk_fma_f32 v[130:131], v[134:135], v[232:233], v[130:131]
	v_pk_fma_f32 v[132:133], v[136:137], v[234:235], v[132:133]
	v_pk_fma_f32 v[114:115], v[118:119], v[50:51], v[114:115]
	v_pk_fma_f32 v[116:117], v[120:121], v[52:53], v[116:117]
	v_permlane32_swap_b32_e32 v122, v130
	v_permlane32_swap_b32_e32 v123, v131
	v_permlane32_swap_b32_e32 v124, v132
	v_permlane32_swap_b32_e32 v125, v133
	v_permlane32_swap_b32_e32 v106, v114
	v_permlane32_swap_b32_e32 v107, v115
	v_permlane32_swap_b32_e32 v108, v116
	v_permlane32_swap_b32_e32 v109, v117
	v_cvt_pk_bf16_f32 v134, v122, v123
	v_cvt_pk_bf16_f32 v135, v124, v125
	v_cvt_pk_bf16_f32 v136, v130, v131
	v_cvt_pk_bf16_f32 v137, v132, v133
	v_add_u32_e32 v246, 0x0, v219
	global_store_dwordx4 v246, v[134:137], s[8:9]
	v_cvt_pk_bf16_f32 v118, v106, v107
	v_cvt_pk_bf16_f32 v119, v108, v109
	v_cvt_pk_bf16_f32 v120, v114, v115
	v_cvt_pk_bf16_f32 v121, v116, v117
	v_add_u32_e32 v247, 0xc000, v219
	global_store_dwordx4 v247, v[118:121], s[8:9]
	s_waitcnt vmcnt(18)
	v_permlane32_swap_b32_e32 v102, v98
	v_permlane32_swap_b32_e32 v103, v99
	v_permlane32_swap_b32_e32 v104, v100
	v_permlane32_swap_b32_e32 v105, v101
	v_permlane32_swap_b32_e32 v86, v82
	v_permlane32_swap_b32_e32 v87, v83
	v_permlane32_swap_b32_e32 v88, v84
	v_permlane32_swap_b32_e32 v89, v85
	v_pk_mul_f32 v[90:91], v[102:103], v[54:55]
	v_pk_mul_f32 v[92:93], v[104:105], v[56:57]
	v_pk_mul_f32 v[74:75], v[86:87], v[188:189]
	v_pk_mul_f32 v[76:77], v[88:89], v[190:191]
	v_pk_fma_f32 v[90:91], v[98:99], v[184:185], v[90:91] neg_lo:[1,0,0] neg_hi:[1,0,0]
	v_pk_fma_f32 v[92:93], v[100:101], v[186:187], v[92:93] neg_lo:[1,0,0] neg_hi:[1,0,0]
	v_pk_fma_f32 v[74:75], v[82:83], v[214:215], v[74:75] neg_lo:[1,0,0] neg_hi:[1,0,0]
	v_pk_fma_f32 v[76:77], v[84:85], v[216:217], v[76:77] neg_lo:[1,0,0] neg_hi:[1,0,0]
	v_pk_mul_f32 v[98:99], v[98:99], v[54:55]
	v_pk_mul_f32 v[100:101], v[100:101], v[56:57]
	v_pk_mul_f32 v[82:83], v[82:83], v[188:189]
	v_pk_mul_f32 v[84:85], v[84:85], v[190:191]
	v_pk_fma_f32 v[98:99], v[102:103], v[184:185], v[98:99]
	v_pk_fma_f32 v[100:101], v[104:105], v[186:187], v[100:101]
	v_pk_fma_f32 v[82:83], v[86:87], v[214:215], v[82:83]
	v_pk_fma_f32 v[84:85], v[88:89], v[216:217], v[84:85]
	v_permlane32_swap_b32_e32 v90, v98
	v_permlane32_swap_b32_e32 v91, v99
	v_permlane32_swap_b32_e32 v92, v100
	v_permlane32_swap_b32_e32 v93, v101
	v_permlane32_swap_b32_e32 v74, v82
	v_permlane32_swap_b32_e32 v75, v83
	v_permlane32_swap_b32_e32 v76, v84
	v_permlane32_swap_b32_e32 v77, v85
	v_cvt_pk_bf16_f32 v102, v90, v91
	v_cvt_pk_bf16_f32 v103, v92, v93
	v_cvt_pk_bf16_f32 v104, v98, v99
	v_cvt_pk_bf16_f32 v105, v100, v101
	v_add_u32_e32 v246, 0x18000, v219
	global_store_dwordx4 v246, v[102:105], s[8:9]
	v_cvt_pk_bf16_f32 v86, v74, v75
	v_cvt_pk_bf16_f32 v87, v76, v77
	v_cvt_pk_bf16_f32 v88, v82, v83
	v_cvt_pk_bf16_f32 v89, v84, v85
	v_add_u32_e32 v247, 0x24000, v219
	global_store_dwordx4 v247, v[86:89], s[8:9]
	s_waitcnt vmcnt(16)
	v_permlane32_swap_b32_e32 v70, v66
	v_permlane32_swap_b32_e32 v71, v67
	v_permlane32_swap_b32_e32 v72, v68
	v_permlane32_swap_b32_e32 v73, v69
	v_permlane32_swap_b32_e32 v46, v42
	v_permlane32_swap_b32_e32 v47, v43
	v_permlane32_swap_b32_e32 v48, v44
	v_permlane32_swap_b32_e32 v49, v45
	v_pk_mul_f32 v[58:59], v[70:71], v[150:151]
	v_pk_mul_f32 v[60:61], v[72:73], v[152:153]
	v_pk_mul_f32 v[34:35], v[46:47], v[158:159]
	v_pk_mul_f32 v[36:37], v[48:49], v[160:161]
	v_pk_fma_f32 v[58:59], v[66:67], v[154:155], v[58:59] neg_lo:[1,0,0] neg_hi:[1,0,0]
	v_pk_fma_f32 v[60:61], v[68:69], v[156:157], v[60:61] neg_lo:[1,0,0] neg_hi:[1,0,0]
	v_pk_fma_f32 v[34:35], v[42:43], v[162:163], v[34:35] neg_lo:[1,0,0] neg_hi:[1,0,0]
	v_pk_fma_f32 v[36:37], v[44:45], v[164:165], v[36:37] neg_lo:[1,0,0] neg_hi:[1,0,0]
	v_pk_mul_f32 v[66:67], v[66:67], v[150:151]
	v_pk_mul_f32 v[68:69], v[68:69], v[152:153]
	v_pk_mul_f32 v[42:43], v[42:43], v[158:159]
	v_pk_mul_f32 v[44:45], v[44:45], v[160:161]
	v_pk_fma_f32 v[66:67], v[70:71], v[154:155], v[66:67]
	v_pk_fma_f32 v[68:69], v[72:73], v[156:157], v[68:69]
	v_pk_fma_f32 v[42:43], v[46:47], v[162:163], v[42:43]
	v_pk_fma_f32 v[44:45], v[48:49], v[164:165], v[44:45]
	v_permlane32_swap_b32_e32 v58, v66
	v_permlane32_swap_b32_e32 v59, v67
	v_permlane32_swap_b32_e32 v60, v68
	v_permlane32_swap_b32_e32 v61, v69
	v_permlane32_swap_b32_e32 v34, v42
	v_permlane32_swap_b32_e32 v35, v43
	v_permlane32_swap_b32_e32 v36, v44
	v_permlane32_swap_b32_e32 v37, v45
	v_cvt_pk_bf16_f32 v70, v58, v59
	v_cvt_pk_bf16_f32 v71, v60, v61
	v_cvt_pk_bf16_f32 v72, v66, v67
	v_cvt_pk_bf16_f32 v73, v68, v69
	v_add_u32_e32 v246, 0x60000, v219
	global_store_dwordx4 v246, v[70:73], s[8:9]
	v_cvt_pk_bf16_f32 v46, v34, v35
	v_cvt_pk_bf16_f32 v47, v36, v37
	v_cvt_pk_bf16_f32 v48, v42, v43
	v_cvt_pk_bf16_f32 v49, v44, v45
	v_add_u32_e32 v247, 0x6c000, v219
	global_store_dwordx4 v247, v[46:49], s[8:9]
	s_waitcnt vmcnt(14)
	v_permlane32_swap_b32_e32 v30, v26
	v_permlane32_swap_b32_e32 v31, v27
	v_permlane32_swap_b32_e32 v32, v28
	v_permlane32_swap_b32_e32 v33, v29
	v_permlane32_swap_b32_e32 v14, v10
	v_permlane32_swap_b32_e32 v15, v11
	v_permlane32_swap_b32_e32 v16, v12
	v_permlane32_swap_b32_e32 v17, v13
	v_pk_mul_f32 v[18:19], v[30:31], v[166:167]
	v_pk_mul_f32 v[20:21], v[32:33], v[168:169]
	v_pk_mul_f32 v[2:3], v[14:15], v[174:175]
	v_pk_mul_f32 v[4:5], v[16:17], v[176:177]
	v_pk_fma_f32 v[18:19], v[26:27], v[170:171], v[18:19] neg_lo:[1,0,0] neg_hi:[1,0,0]
	v_pk_fma_f32 v[20:21], v[28:29], v[172:173], v[20:21] neg_lo:[1,0,0] neg_hi:[1,0,0]
	v_pk_fma_f32 v[2:3], v[10:11], v[180:181], v[2:3] neg_lo:[1,0,0] neg_hi:[1,0,0]
	v_pk_fma_f32 v[4:5], v[12:13], v[182:183], v[4:5] neg_lo:[1,0,0] neg_hi:[1,0,0]
	v_pk_mul_f32 v[26:27], v[26:27], v[166:167]
	v_pk_mul_f32 v[28:29], v[28:29], v[168:169]
	v_pk_mul_f32 v[10:11], v[10:11], v[174:175]
	v_pk_mul_f32 v[12:13], v[12:13], v[176:177]
	v_pk_fma_f32 v[26:27], v[30:31], v[170:171], v[26:27]
	v_pk_fma_f32 v[28:29], v[32:33], v[172:173], v[28:29]
	v_pk_fma_f32 v[10:11], v[14:15], v[180:181], v[10:11]
	v_pk_fma_f32 v[12:13], v[16:17], v[182:183], v[12:13]
	v_permlane32_swap_b32_e32 v18, v26
	v_permlane32_swap_b32_e32 v19, v27
	v_permlane32_swap_b32_e32 v20, v28
	v_permlane32_swap_b32_e32 v21, v29
	v_permlane32_swap_b32_e32 v2, v10
	v_permlane32_swap_b32_e32 v3, v11
	v_permlane32_swap_b32_e32 v4, v12
	v_permlane32_swap_b32_e32 v5, v13
	v_cvt_pk_bf16_f32 v30, v18, v19
	v_cvt_pk_bf16_f32 v31, v20, v21
	v_cvt_pk_bf16_f32 v32, v26, v27
	v_cvt_pk_bf16_f32 v33, v28, v29
	v_add_u32_e32 v246, 0x78000, v219
	global_store_dwordx4 v246, v[30:33], s[8:9]
	v_cvt_pk_bf16_f32 v14, v2, v3
	v_cvt_pk_bf16_f32 v15, v4, v5
	v_cvt_pk_bf16_f32 v16, v10, v11
	v_cvt_pk_bf16_f32 v17, v12, v13
	v_add_u32_e32 v247, 0x84000, v219
	global_store_dwordx4 v247, v[14:17], s[8:9]
	s_branch .Luq_end
.Luq_r1:
	v_and_b32_e32 v246, 1, v218
	v_and_b32_e32 v247, 2, v218
	v_lshlrev_b32_e32 v244, 6, v0
	v_lshl_add_u32 v244, v246, 5, v244
	v_lshl_add_u32 v244, v247, 3, v244
	v_add_u32_e32 v245, 0x2000, v244
	global_load_dwordx4 v[228:231], v244, s[10:11]
	global_load_dwordx4 v[232:235], v244, s[12:13]
	global_load_dwordx4 v[236:239], v244, s[10:11] offset:1024
	global_load_dwordx4 v[50:53], v244, s[12:13] offset:1024
	global_load_dwordx4 v[54:57], v244, s[10:11] offset:2048
	global_load_dwordx4 v[184:187], v244, s[12:13] offset:2048
	global_load_dwordx4 v[188:191], v244, s[10:11] offset:3072
	global_load_dwordx4 v[214:217], v244, s[12:13] offset:3072
	global_load_dwordx4 v[150:153], v245, s[10:11]
	global_load_dwordx4 v[154:157], v245, s[12:13]
	global_load_dwordx4 v[158:161], v245, s[10:11] offset:1024
	global_load_dwordx4 v[162:165], v245, s[12:13] offset:1024
	global_load_dwordx4 v[166:169], v245, s[10:11] offset:2048
	global_load_dwordx4 v[170:173], v245, s[12:13] offset:2048
	global_load_dwordx4 v[174:177], v245, s[10:11] offset:3072
	global_load_dwordx4 v[180:183], v245, s[12:13] offset:3072
	v_add_f32_e32 v194, v195, v194
	v_add_f32_e32 v196, v196, v197
	v_add_f32_e32 v198, v199, v198
	v_add_f32_e32 v200, v200, v201
	v_add_f32_e32 v202, v203, v202
	v_add_f32_e32 v204, v204, v205
	v_add_f32_e32 v206, v207, v206
	v_add_f32_e32 v208, v208, v209
	v_add_f32_e32 v194, v194, v196
	v_add_f32_e32 v198, v198, v200
	v_add_f32_e32 v202, v202, v204
	v_add_f32_e32 v206, v206, v208
	v_cndmask_b32_e32 v221, 0, v221, vcc
	v_cndmask_b32_e32 v222, 0, v222, vcc
	v_cndmask_b32_e32 v223, 0, v223, vcc
	v_cndmask_b32_e32 v224, 0, v224, vcc
	v_cndmask_b32_e32 v194, 0, v194, vcc
	v_cndmask_b32_e32 v198, 0, v198, vcc
	v_cndmask_b32_e32 v202, 0, v202, vcc
	v_cndmask_b32_e32 v206, 0, v206, vcc
	ds_swizzle_b32 v195, v221 offset:swizzle(SWAP,16)
	ds_swizzle_b32 v196, v222 offset:swizzle(SWAP,16)
	ds_swizzle_b32 v199, v223 offset:swizzle(SWAP,16)
	ds_swizzle_b32 v200, v224 offset:swizzle(SWAP,16)
	ds_swizzle_b32 v203, v194 offset:swizzle(SWAP,16)
	ds_swizzle_b32 v204, v198 offset:swizzle(SWAP,16)
	ds_swizzle_b32 v207, v202 offset:swizzle(SWAP,16)
	ds_swizzle_b32 v208, v206 offset:swizzle(SWAP,16)
	s_waitcnt lgkmcnt(0)
	v_add_f32_e32 v221, v221, v195
	v_add_f32_e32 v222, v222, v196
	v_add_f32_e32 v223, v223, v199
	v_add_f32_e32 v224, v224, v200
	v_add_f32_e32 v194, v194, v203
	v_add_f32_e32 v198, v198, v204
	v_add_f32_e32 v202, v202, v207
	v_add_f32_e32 v206, v206, v208
	v_mov_b32_e32 v197, v221
	v_mov_b32_e32 v201, v222
	v_mov_b32_e32 v205, v223
	v_mov_b32_e32 v209, v224
	v_mov_b32_e32 v240, v194
	v_mov_b32_e32 v241, v198
	v_mov_b32_e32 v242, v202
	v_mov_b32_e32 v243, v206
	v_permlane32_swap_b32_e32 v221, v197
	v_permlane32_swap_b32_e32 v222, v201
	v_permlane32_swap_b32_e32 v223, v205
	v_permlane32_swap_b32_e32 v224, v209
	v_permlane32_swap_b32_e32 v194, v240
	v_permlane32_swap_b32_e32 v198, v241
	v_permlane32_swap_b32_e32 v202, v242
	v_permlane32_swap_b32_e32 v206, v243
	v_add_f32_e32 v221, v221, v197
	v_add_f32_e32 v222, v222, v201
	v_add_f32_e32 v223, v223, v205
	v_add_f32_e32 v224, v224, v209
	v_add_f32_e32 v194, v194, v240
	v_add_f32_e32 v198, v198, v241
	v_add_f32_e32 v202, v202, v242
	v_add_f32_e32 v206, v206, v243
	v_fmamk_f32 v221, v221, 0x3b2aaaab, v192
	v_fmamk_f32 v222, v222, 0x3b2aaaab, v192
	v_fmamk_f32 v223, v223, 0x3b2aaaab, v192
	v_fmamk_f32 v224, v224, 0x3b2aaaab, v192
	v_fmamk_f32 v194, v194, 0x3b2aaaab, v192
	v_fmamk_f32 v198, v198, 0x3b2aaaab, v192
	v_fmamk_f32 v202, v202, 0x3b2aaaab, v192
	v_fmamk_f32 v206, v206, 0x3b2aaaab, v192
	v_rsq_f32_e32 v221, v221
	v_rsq_f32_e32 v222, v222
	v_rsq_f32_e32 v223, v223
	v_rsq_f32_e32 v224, v224
	v_rsq_f32_e32 v194, v194
	v_rsq_f32_e32 v198, v198
	v_rsq_f32_e32 v202, v202
	v_rsq_f32_e32 v206, v206
	v_mul_f32_e32 v221, 0x3e16c740, v221
	v_mul_f32_e32 v222, 0x3e16c740, v222
	v_mul_f32_e32 v223, 0x3e16c740, v223
	v_mul_f32_e32 v224, 0x3e16c740, v224
	v_mul_f32_e32 v194, 0x3e16c740, v194
	v_mul_f32_e32 v198, 0x3e16c740, v198
	v_mul_f32_e32 v202, 0x3e16c740, v202
	v_mul_f32_e32 v206, 0x3e16c740, v206
	v_pk_mul_f32 v[134:135], v[134:135], v[220:221] op_sel:[0,1] op_sel_hi:[1,1]
	v_pk_mul_f32 v[136:137], v[136:137], v[220:221] op_sel:[0,1] op_sel_hi:[1,1]
	v_pk_mul_f32 v[130:131], v[130:131], v[220:221] op_sel:[0,1] op_sel_hi:[1,1]
	v_pk_mul_f32 v[132:133], v[132:133], v[220:221] op_sel:[0,1] op_sel_hi:[1,1]
	v_pk_mul_f32 v[126:127], v[126:127], v[220:221] op_sel:[0,1] op_sel_hi:[1,1]
	v_pk_mul_f32 v[128:129], v[128:129], v[220:221] op_sel:[0,1] op_sel_hi:[1,1]
	v_pk_mul_f32 v[122:123], v[122:123], v[220:221] op_sel:[0,1] op_sel_hi:[1,1]
	v_pk_mul_f32 v[124:125], v[124:125], v[220:221] op_sel:[0,1] op_sel_hi:[1,1]
	v_cvt_pk_bf16_f32 v134, v134, v135
	v_cvt_pk_bf16_f32 v135, v136, v137
	v_cvt_pk_bf16_f32 v136, v130, v131
	v_cvt_pk_bf16_f32 v137, v132, v133
	v_add_u32_e32 v246, 0x0, v219
	global_store_dwordx4 v246, v[134:137], s[8:9]
	v_pk_mul_f32 v[118:119], v[118:119], v[222:223] op_sel_hi:[1,0]
	v_pk_mul_f32 v[120:121], v[120:121], v[222:223] op_sel_hi:[1,0]
	v_pk_mul_f32 v[114:115], v[114:115], v[222:223] op_sel_hi:[1,0]
	v_pk_mul_f32 v[116:117], v[116:117], v[222:223] op_sel_hi:[1,0]
	v_pk_mul_f32 v[110:111], v[110:111], v[222:223] op_sel_hi:[1,0]
	v_pk_mul_f32 v[112:113], v[112:113], v[222:223] op_sel_hi:[1,0]
	v_pk_mul_f32 v[106:107], v[106:107], v[222:223] op_sel_hi:[1,0]
	v_pk_mul_f32 v[108:109], v[108:109], v[222:223] op_sel_hi:[1,0]
	v_cvt_pk_bf16_f32 v118, v118, v119
	v_cvt_pk_bf16_f32 v119, v120, v121
	v_cvt_pk_bf16_f32 v120, v114, v115
	v_cvt_pk_bf16_f32 v121, v116, v117
	v_add_u32_e32 v247, 0xc000, v219
	global_store_dwordx4 v247, v[118:121], s[8:9]
	v_pk_mul_f32 v[102:103], v[102:103], v[222:223] op_sel:[0,1] op_sel_hi:[1,1]
	v_pk_mul_f32 v[104:105], v[104:105], v[222:223] op_sel:[0,1] op_sel_hi:[1,1]
	v_pk_mul_f32 v[98:99], v[98:99], v[222:223] op_sel:[0,1] op_sel_hi:[1,1]
	v_pk_mul_f32 v[100:101], v[100:101], v[222:223] op_sel:[0,1] op_sel_hi:[1,1]
	v_pk_mul_f32 v[94:95], v[94:95], v[222:223] op_sel:[0,1] op_sel_hi:[1,1]
	v_pk_mul_f32 v[96:97], v[96:97], v[222:223] op_sel:[0,1] op_sel_hi:[1,1]
	v_pk_mul_f32 v[90:91], v[90:91], v[222:223] op_sel:[0,1] op_sel_hi:[1,1]
	v_pk_mul_f32 v[92:93], v[92:93], v[222:223] op_sel:[0,1] op_sel_hi:[1,1]
	v_cvt_pk_bf16_f32 v102, v102, v103
	v_cvt_pk_bf16_f32 v103, v104, v105
	v_cvt_pk_bf16_f32 v104, v98, v99
	v_cvt_pk_bf16_f32 v105, v100, v101
	v_add_u32_e32 v246, 0x18000, v219
	global_store_dwordx4 v246, v[102:105], s[8:9]
	v_pk_mul_f32 v[86:87], v[86:87], v[224:225] op_sel_hi:[1,0]
	v_pk_mul_f32 v[88:89], v[88:89], v[224:225] op_sel_hi:[1,0]
	v_pk_mul_f32 v[82:83], v[82:83], v[224:225] op_sel_hi:[1,0]
	v_pk_mul_f32 v[84:85], v[84:85], v[224:225] op_sel_hi:[1,0]
	v_pk_mul_f32 v[78:79], v[78:79], v[224:225] op_sel_hi:[1,0]
	v_pk_mul_f32 v[80:81], v[80:81], v[224:225] op_sel_hi:[1,0]
	v_pk_mul_f32 v[74:75], v[74:75], v[224:225] op_sel_hi:[1,0]
	v_pk_mul_f32 v[76:77], v[76:77], v[224:225] op_sel_hi:[1,0]
	v_cvt_pk_bf16_f32 v86, v86, v87
	v_cvt_pk_bf16_f32 v87, v88, v89
	v_cvt_pk_bf16_f32 v88, v82, v83
	v_cvt_pk_bf16_f32 v89, v84, v85
	v_add_u32_e32 v247, 0x24000, v219
	global_store_dwordx4 v247, v[86:89], s[8:9]
	v_pk_mul_f32 v[70:71], v[70:71], v[194:195] op_sel_hi:[1,0]
	v_pk_mul_f32 v[72:73], v[72:73], v[194:195] op_sel_hi:[1,0]
	v_pk_mul_f32 v[66:67], v[66:67], v[194:195] op_sel_hi:[1,0]
	v_pk_mul_f32 v[68:69], v[68:69], v[194:195] op_sel_hi:[1,0]
	v_pk_mul_f32 v[62:63], v[62:63], v[194:195] op_sel_hi:[1,0]
	v_pk_mul_f32 v[64:65], v[64:65], v[194:195] op_sel_hi:[1,0]
	v_pk_mul_f32 v[58:59], v[58:59], v[194:195] op_sel_hi:[1,0]
	v_pk_mul_f32 v[60:61], v[60:61], v[194:195] op_sel_hi:[1,0]
	v_cvt_pk_bf16_f32 v70, v70, v71
	v_cvt_pk_bf16_f32 v71, v72, v73
	v_cvt_pk_bf16_f32 v72, v66, v67
	v_cvt_pk_bf16_f32 v73, v68, v69
	v_add_u32_e32 v246, 0x60000, v219
	global_store_dwordx4 v246, v[70:73], s[8:9]
	v_pk_mul_f32 v[46:47], v[46:47], v[198:199] op_sel_hi:[1,0]
	v_pk_mul_f32 v[48:49], v[48:49], v[198:199] op_sel_hi:[1,0]
	v_pk_mul_f32 v[42:43], v[42:43], v[198:199] op_sel_hi:[1,0]
	v_pk_mul_f32 v[44:45], v[44:45], v[198:199] op_sel_hi:[1,0]
	v_pk_mul_f32 v[38:39], v[38:39], v[198:199] op_sel_hi:[1,0]
	v_pk_mul_f32 v[40:41], v[40:41], v[198:199] op_sel_hi:[1,0]
	v_pk_mul_f32 v[34:35], v[34:35], v[198:199] op_sel_hi:[1,0]
	v_pk_mul_f32 v[36:37], v[36:37], v[198:199] op_sel_hi:[1,0]
	v_cvt_pk_bf16_f32 v46, v46, v47
	v_cvt_pk_bf16_f32 v47, v48, v49
	v_cvt_pk_bf16_f32 v48, v42, v43
	v_cvt_pk_bf16_f32 v49, v44, v45
	v_add_u32_e32 v247, 0x6c000, v219
	global_store_dwordx4 v247, v[46:49], s[8:9]
	v_pk_mul_f32 v[30:31], v[30:31], v[202:203] op_sel_hi:[1,0]
	v_pk_mul_f32 v[32:33], v[32:33], v[202:203] op_sel_hi:[1,0]
	v_pk_mul_f32 v[26:27], v[26:27], v[202:203] op_sel_hi:[1,0]
	v_pk_mul_f32 v[28:29], v[28:29], v[202:203] op_sel_hi:[1,0]
	v_pk_mul_f32 v[22:23], v[22:23], v[202:203] op_sel_hi:[1,0]
	v_pk_mul_f32 v[24:25], v[24:25], v[202:203] op_sel_hi:[1,0]
	v_pk_mul_f32 v[18:19], v[18:19], v[202:203] op_sel_hi:[1,0]
	v_pk_mul_f32 v[20:21], v[20:21], v[202:203] op_sel_hi:[1,0]
	v_cvt_pk_bf16_f32 v30, v30, v31
	v_cvt_pk_bf16_f32 v31, v32, v33
	v_cvt_pk_bf16_f32 v32, v26, v27
	v_cvt_pk_bf16_f32 v33, v28, v29
	v_add_u32_e32 v246, 0x78000, v219
	global_store_dwordx4 v246, v[30:33], s[8:9]
	v_pk_mul_f32 v[14:15], v[14:15], v[206:207] op_sel_hi:[1,0]
	v_pk_mul_f32 v[16:17], v[16:17], v[206:207] op_sel_hi:[1,0]
	v_pk_mul_f32 v[10:11], v[10:11], v[206:207] op_sel_hi:[1,0]
	v_pk_mul_f32 v[12:13], v[12:13], v[206:207] op_sel_hi:[1,0]
	v_pk_mul_f32 v[6:7], v[6:7], v[206:207] op_sel_hi:[1,0]
	v_pk_mul_f32 v[8:9], v[8:9], v[206:207] op_sel_hi:[1,0]
	v_pk_mul_f32 v[2:3], v[2:3], v[206:207] op_sel_hi:[1,0]
	v_pk_mul_f32 v[4:5], v[4:5], v[206:207] op_sel_hi:[1,0]
	v_cvt_pk_bf16_f32 v14, v14, v15
	v_cvt_pk_bf16_f32 v15, v16, v17
	v_cvt_pk_bf16_f32 v16, v10, v11
	v_cvt_pk_bf16_f32 v17, v12, v13
	v_add_u32_e32 v247, 0x84000, v219
	global_store_dwordx4 v247, v[14:17], s[8:9]
	s_waitcnt vmcnt(20)
	v_permlane32_swap_b32_e32 v126, v122
	v_permlane32_swap_b32_e32 v127, v123
	v_permlane32_swap_b32_e32 v128, v124
	v_permlane32_swap_b32_e32 v129, v125
	v_permlane32_swap_b32_e32 v110, v106
	v_permlane32_swap_b32_e32 v111, v107
	v_permlane32_swap_b32_e32 v112, v108
	v_permlane32_swap_b32_e32 v113, v109
	v_pk_mul_f32 v[130:131], v[126:127], v[228:229]
	v_pk_mul_f32 v[132:133], v[128:129], v[230:231]
	v_pk_mul_f32 v[114:115], v[110:111], v[236:237]
	v_pk_mul_f32 v[116:117], v[112:113], v[238:239]
	v_pk_fma_f32 v[130:131], v[122:123], v[232:233], v[130:131] neg_lo:[1,0,0] neg_hi:[1,0,0]
	v_pk_fma_f32 v[132:133], v[124:125], v[234:235], v[132:133] neg_lo:[1,0,0] neg_hi:[1,0,0]
	v_pk_fma_f32 v[114:115], v[106:107], v[50:51], v[114:115] neg_lo:[1,0,0] neg_hi:[1,0,0]
	v_pk_fma_f32 v[116:117], v[108:109], v[52:53], v[116:117] neg_lo:[1,0,0] neg_hi:[1,0,0]
	v_pk_mul_f32 v[122:123], v[122:123], v[228:229]
	v_pk_mul_f32 v[124:125], v[124:125], v[230:231]
	v_pk_mul_f32 v[106:107], v[106:107], v[236:237]
	v_pk_mul_f32 v[108:109], v[108:109], v[238:239]
	v_pk_fma_f32 v[122:123], v[126:127], v[232:233], v[122:123]
	v_pk_fma_f32 v[124:125], v[128:129], v[234:235], v[124:125]
	v_pk_fma_f32 v[106:107], v[110:111], v[50:51], v[106:107]
	v_pk_fma_f32 v[108:109], v[112:113], v[52:53], v[108:109]
	v_permlane32_swap_b32_e32 v130, v122
	v_permlane32_swap_b32_e32 v131, v123
	v_permlane32_swap_b32_e32 v132, v124
	v_permlane32_swap_b32_e32 v133, v125
	v_permlane32_swap_b32_e32 v114, v106
	v_permlane32_swap_b32_e32 v115, v107
	v_permlane32_swap_b32_e32 v116, v108
	v_permlane32_swap_b32_e32 v117, v109
	v_cvt_pk_bf16_f32 v126, v130, v131
	v_cvt_pk_bf16_f32 v127, v132, v133
	v_cvt_pk_bf16_f32 v128, v122, v123
	v_cvt_pk_bf16_f32 v129, v124, v125
	v_add_u32_e32 v246, 0x0, v219
	global_store_dwordx4 v246, v[126:129], s[8:9] offset:256
	v_cvt_pk_bf16_f32 v110, v114, v115
	v_cvt_pk_bf16_f32 v111, v116, v117
	v_cvt_pk_bf16_f32 v112, v106, v107
	v_cvt_pk_bf16_f32 v113, v108, v109
	v_add_u32_e32 v247, 0xc000, v219
	global_store_dwordx4 v247, v[110:113], s[8:9] offset:256
	s_waitcnt vmcnt(18)
	v_permlane32_swap_b32_e32 v94, v90
	v_permlane32_swap_b32_e32 v95, v91
	v_permlane32_swap_b32_e32 v96, v92
	v_permlane32_swap_b32_e32 v97, v93
	v_permlane32_swap_b32_e32 v78, v74
	v_permlane32_swap_b32_e32 v79, v75
	v_permlane32_swap_b32_e32 v80, v76
	v_permlane32_swap_b32_e32 v81, v77
	v_pk_mul_f32 v[98:99], v[94:95], v[54:55]
	v_pk_mul_f32 v[100:101], v[96:97], v[56:57]
	v_pk_mul_f32 v[82:83], v[78:79], v[188:189]
	v_pk_mul_f32 v[84:85], v[80:81], v[190:191]
	v_pk_fma_f32 v[98:99], v[90:91], v[184:185], v[98:99] neg_lo:[1,0,0] neg_hi:[1,0,0]
	v_pk_fma_f32 v[100:101], v[92:93], v[186:187], v[100:101] neg_lo:[1,0,0] neg_hi:[1,0,0]
	v_pk_fma_f32 v[82:83], v[74:75], v[214:215], v[82:83] neg_lo:[1,0,0] neg_hi:[1,0,0]
	v_pk_fma_f32 v[84:85], v[76:77], v[216:217], v[84:85] neg_lo:[1,0,0] neg_hi:[1,0,0]
	v_pk_mul_f32 v[90:91], v[90:91], v[54:55]
	v_pk_mul_f32 v[92:93], v[92:93], v[56:57]
	v_pk_mul_f32 v[74:75], v[74:75], v[188:189]
	v_pk_mul_f32 v[76:77], v[76:77], v[190:191]
	v_pk_fma_f32 v[90:91], v[94:95], v[184:185], v[90:91]
	v_pk_fma_f32 v[92:93], v[96:97], v[186:187], v[92:93]
	v_pk_fma_f32 v[74:75], v[78:79], v[214:215], v[74:75]
	v_pk_fma_f32 v[76:77], v[80:81], v[216:217], v[76:77]
	v_permlane32_swap_b32_e32 v98, v90
	v_permlane32_swap_b32_e32 v99, v91
	v_permlane32_swap_b32_e32 v100, v92
	v_permlane32_swap_b32_e32 v101, v93
	v_permlane32_swap_b32_e32 v82, v74
	v_permlane32_swap_b32_e32 v83, v75
	v_permlane32_swap_b32_e32 v84, v76
	v_permlane32_swap_b32_e32 v85, v77
	v_cvt_pk_bf16_f32 v94, v98, v99
	v_cvt_pk_bf16_f32 v95, v100, v101
	v_cvt_pk_bf16_f32 v96, v90, v91
	v_cvt_pk_bf16_f32 v97, v92, v93
	v_add_u32_e32 v246, 0x18000, v219
	global_store_dwordx4 v246, v[94:97], s[8:9] offset:256
	v_cvt_pk_bf16_f32 v78, v82, v83
	v_cvt_pk_bf16_f32 v79, v84, v85
	v_cvt_pk_bf16_f32 v80, v74, v75
	v_cvt_pk_bf16_f32 v81, v76, v77
	v_add_u32_e32 v247, 0x24000, v219
	global_store_dwordx4 v247, v[78:81], s[8:9] offset:256
	s_waitcnt vmcnt(16)
	v_permlane32_swap_b32_e32 v62, v58
	v_permlane32_swap_b32_e32 v63, v59
	v_permlane32_swap_b32_e32 v64, v60
	v_permlane32_swap_b32_e32 v65, v61
	v_permlane32_swap_b32_e32 v38, v34
	v_permlane32_swap_b32_e32 v39, v35
	v_permlane32_swap_b32_e32 v40, v36
	v_permlane32_swap_b32_e32 v41, v37
	v_pk_mul_f32 v[66:67], v[62:63], v[150:151]
	v_pk_mul_f32 v[68:69], v[64:65], v[152:153]
	v_pk_mul_f32 v[42:43], v[38:39], v[158:159]
	v_pk_mul_f32 v[44:45], v[40:41], v[160:161]
	v_pk_fma_f32 v[66:67], v[58:59], v[154:155], v[66:67] neg_lo:[1,0,0] neg_hi:[1,0,0]
	v_pk_fma_f32 v[68:69], v[60:61], v[156:157], v[68:69] neg_lo:[1,0,0] neg_hi:[1,0,0]
	v_pk_fma_f32 v[42:43], v[34:35], v[162:163], v[42:43] neg_lo:[1,0,0] neg_hi:[1,0,0]
	v_pk_fma_f32 v[44:45], v[36:37], v[164:165], v[44:45] neg_lo:[1,0,0] neg_hi:[1,0,0]
	v_pk_mul_f32 v[58:59], v[58:59], v[150:151]
	v_pk_mul_f32 v[60:61], v[60:61], v[152:153]
	v_pk_mul_f32 v[34:35], v[34:35], v[158:159]
	v_pk_mul_f32 v[36:37], v[36:37], v[160:161]
	v_pk_fma_f32 v[58:59], v[62:63], v[154:155], v[58:59]
	v_pk_fma_f32 v[60:61], v[64:65], v[156:157], v[60:61]
	v_pk_fma_f32 v[34:35], v[38:39], v[162:163], v[34:35]
	v_pk_fma_f32 v[36:37], v[40:41], v[164:165], v[36:37]
	v_permlane32_swap_b32_e32 v66, v58
	v_permlane32_swap_b32_e32 v67, v59
	v_permlane32_swap_b32_e32 v68, v60
	v_permlane32_swap_b32_e32 v69, v61
	v_permlane32_swap_b32_e32 v42, v34
	v_permlane32_swap_b32_e32 v43, v35
	v_permlane32_swap_b32_e32 v44, v36
	v_permlane32_swap_b32_e32 v45, v37
	v_cvt_pk_bf16_f32 v62, v66, v67
	v_cvt_pk_bf16_f32 v63, v68, v69
	v_cvt_pk_bf16_f32 v64, v58, v59
	v_cvt_pk_bf16_f32 v65, v60, v61
	v_add_u32_e32 v246, 0x60000, v219
	global_store_dwordx4 v246, v[62:65], s[8:9] offset:256
	v_cvt_pk_bf16_f32 v38, v42, v43
	v_cvt_pk_bf16_f32 v39, v44, v45
	v_cvt_pk_bf16_f32 v40, v34, v35
	v_cvt_pk_bf16_f32 v41, v36, v37
	v_add_u32_e32 v247, 0x6c000, v219
	global_store_dwordx4 v247, v[38:41], s[8:9] offset:256
	s_waitcnt vmcnt(14)
	v_permlane32_swap_b32_e32 v22, v18
	v_permlane32_swap_b32_e32 v23, v19
	v_permlane32_swap_b32_e32 v24, v20
	v_permlane32_swap_b32_e32 v25, v21
	v_permlane32_swap_b32_e32 v6, v2
	v_permlane32_swap_b32_e32 v7, v3
	v_permlane32_swap_b32_e32 v8, v4
	v_permlane32_swap_b32_e32 v9, v5
	v_pk_mul_f32 v[26:27], v[22:23], v[166:167]
	v_pk_mul_f32 v[28:29], v[24:25], v[168:169]
	v_pk_mul_f32 v[10:11], v[6:7], v[174:175]
	v_pk_mul_f32 v[12:13], v[8:9], v[176:177]
	v_pk_fma_f32 v[26:27], v[18:19], v[170:171], v[26:27] neg_lo:[1,0,0] neg_hi:[1,0,0]
	v_pk_fma_f32 v[28:29], v[20:21], v[172:173], v[28:29] neg_lo:[1,0,0] neg_hi:[1,0,0]
	v_pk_fma_f32 v[10:11], v[2:3], v[180:181], v[10:11] neg_lo:[1,0,0] neg_hi:[1,0,0]
	v_pk_fma_f32 v[12:13], v[4:5], v[182:183], v[12:13] neg_lo:[1,0,0] neg_hi:[1,0,0]
	v_pk_mul_f32 v[18:19], v[18:19], v[166:167]
	v_pk_mul_f32 v[20:21], v[20:21], v[168:169]
	v_pk_mul_f32 v[2:3], v[2:3], v[174:175]
	v_pk_mul_f32 v[4:5], v[4:5], v[176:177]
	v_pk_fma_f32 v[18:19], v[22:23], v[170:171], v[18:19]
	v_pk_fma_f32 v[20:21], v[24:25], v[172:173], v[20:21]
	v_pk_fma_f32 v[2:3], v[6:7], v[180:181], v[2:3]
	v_pk_fma_f32 v[4:5], v[8:9], v[182:183], v[4:5]
	v_permlane32_swap_b32_e32 v26, v18
	v_permlane32_swap_b32_e32 v27, v19
	v_permlane32_swap_b32_e32 v28, v20
	v_permlane32_swap_b32_e32 v29, v21
	v_permlane32_swap_b32_e32 v10, v2
	v_permlane32_swap_b32_e32 v11, v3
	v_permlane32_swap_b32_e32 v12, v4
	v_permlane32_swap_b32_e32 v13, v5
	v_cvt_pk_bf16_f32 v22, v26, v27
	v_cvt_pk_bf16_f32 v23, v28, v29
	v_cvt_pk_bf16_f32 v24, v18, v19
	v_cvt_pk_bf16_f32 v25, v20, v21
	v_add_u32_e32 v246, 0x78000, v219
	global_store_dwordx4 v246, v[22:25], s[8:9] offset:256
	v_cvt_pk_bf16_f32 v6, v10, v11
	v_cvt_pk_bf16_f32 v7, v12, v13
	v_cvt_pk_bf16_f32 v8, v2, v3
	v_cvt_pk_bf16_f32 v9, v4, v5
	v_add_u32_e32 v247, 0x84000, v219
	global_store_dwordx4 v247, v[6:9], s[8:9] offset:256

.LBB0_339:
	v_readlane_b32 s2, v250, 33
	s_mov_b64 s[10:11], s[58:59]
	v_mov_b32_e32 v0, v193
	v_readlane_b32 s3, v250, 34
	s_andn2_b64 vcc, exec, s[2:3]
	v_readfirstlane_b32 s12, v0
	s_cbranch_vccnz .LBB0_441
	v_lshlrev_b32_e32 v2, 4, v0
	v_add_u32_e32 v3, 0x2000, v2
	v_ashrrev_i32_e32 v4, 31, v3
	v_lshrrev_b32_e32 v4, 22, v4
	v_add_u32_e32 v4, v3, v4
	v_ashrrev_i32_e32 v4, 10, v4
	v_mul_i32_i24_e32 v5, 0x400, v4
	v_sub_u32_e32 v3, v3, v5
	v_lshrrev_b32_e32 v5, 4, v3
	v_bitop3_b32 v3, v5, v3, 32 bitop3:0x6c
	v_ashrrev_i32_e32 v5, 31, v3
	v_lshrrev_b32_e32 v5, 26, v5
	s_add_u32 s4, s10, 0x11100000
	v_add_u32_e32 v5, v3, v5
	v_lshlrev_b32_e32 v7, 3, v4
	s_addc_u32 s28, s11, 0
	s_lshl_b64 s[2:3], s[30:31], 20
	v_ashrrev_i32_e32 v6, 6, v5
	v_and_b32_e32 v7, -16, v7
	v_and_b32_e32 v5, 0xc0, v5
	s_add_u32 s0, s10, s2
	v_add_u32_e32 v7, v6, v7
	v_lshlrev_b32_e32 v4, 5, v4
	v_sub_u32_e32 v3, v3, v5
	s_addc_u32 s2, s11, s3
	v_and_b32_e32 v6, 3, v6
	s_mov_b32 s3, 0x7fffe0
	v_lshrrev_b32_e32 v8, 2, v7
	v_lshlrev_b32_e32 v9, 1, v7
	v_and_b32_e32 v4, 32, v4
	v_ashrrev_i16_sdwa v3, v220, sext(v3) dst_sel:DWORD dst_unused:UNUSED_PAD src0_sel:DWORD src1_sel:BYTE_0
	s_add_u32 s29, s0, 0x1040000
	v_and_or_b32 v6, v7, s3, v6
	v_and_b32_e32 v8, 4, v8
	v_and_b32_e32 v9, 24, v9
	v_add_u32_sdwa v3, v4, sext(v3) dst_sel:DWORD dst_unused:UNUSED_PAD src0_sel:DWORD src1_sel:WORD_0
	s_addc_u32 s51, s2, 0
	v_or3_b32 v6, v6, v8, v9
	v_lshlrev_b32_e32 v4, 1, v3
	s_movk_i32 s2, 0x300
	v_lshl_add_u32 v136, v6, 9, v4
	v_mul_lo_u32 v4, v7, s2
	v_add_lshl_u32 v138, v3, v4, 1
	v_bfe_i32 v3, v0, 27, 1
	v_lshrrev_b32_e32 v3, 22, v3
	v_add_u32_e32 v3, v2, v3
	v_and_b32_e32 v3, 0xfffffc00, v3
	v_sub_u32_e32 v2, v2, v3
	v_ashrrev_i32_e32 v4, 31, v0
	v_lshrrev_b32_e32 v3, 4, v2
	v_lshrrev_b32_e32 v4, 26, v4
	v_bitop3_b32 v3, v3, v2, 32 bitop3:0x6c
	v_ashrrev_i32_e32 v2, 31, v2
	v_add_u32_e32 v4, v0, v4
	v_lshrrev_b32_e32 v2, 26, v2
	v_ashrrev_i32_e32 v4, 6, v4
	v_add_u32_e32 v2, v3, v2
	v_lshlrev_b32_e32 v5, 3, v4
	v_ashrrev_i32_e32 v2, 6, v2
	v_and_b32_e32 v5, -16, v5
	v_add_u32_e32 v5, v2, v5
	v_and_b32_e32 v6, 3, v2
	v_mul_i32_i24_e32 v2, 64, v2
	v_lshlrev_b32_e32 v4, 5, v4
	v_sub_u32_e32 v2, v3, v2
	v_lshrrev_b32_e32 v7, 2, v5
	v_lshlrev_b32_e32 v8, 1, v5
	v_and_b32_e32 v4, 32, v4
	v_ashrrev_i16_sdwa v2, v220, sext(v2) dst_sel:DWORD dst_unused:UNUSED_PAD src0_sel:DWORD src1_sel:BYTE_0
	v_and_or_b32 v6, v5, s3, v6
	v_and_b32_e32 v7, 4, v7
	v_and_b32_e32 v8, 24, v8
	v_add_u32_sdwa v2, v4, sext(v2) dst_sel:DWORD dst_unused:UNUSED_PAD src0_sel:DWORD src1_sel:WORD_0
	s_ashr_i32 s13, s12, 6
	v_or3_b32 v6, v6, v7, v8
	v_lshlrev_b32_e32 v3, 1, v2
	s_ashr_i32 s0, s12, 8
	s_lshl_b32 s54, s13, 10
	v_lshl_add_u32 v140, v6, 9, v3
	v_mul_lo_u32 v3, v5, s2
	v_readlane_b32 s2, v251, 22
	s_nop 3
	s_cmpk_lt_u32 s2, 0x80
	v_readlane_b32 s2, v249, 21
	v_readlane_b32 s3, v249, 22
	s_nop 1
	s_cbranch_scc1 .Lukvb_b0
	s_add_u32 s2, s2, 0x80000
	s_addc_u32 s3, s3, 0
.Lukvb_b0:
	s_add_u32 s40, s29, s2
	s_addc_u32 s41, s51, s3
	s_add_i32 s34, s54, 0
	s_add_i32 m0, s34, 0x10000
	v_add_lshl_u32 v142, v2, v3, 1
	global_load_lds_dwordx4 v140, s[40:41]
	s_add_i32 m0, s34, 0x12000
	s_add_u32 s2, s40, 0x10000
	global_load_lds_dwordx4 v136, s[40:41]
	s_addc_u32 s3, s41, 0
	s_add_i32 m0, s34, 0x14000
	v_mov_b32_e32 v141, v1
	global_load_lds_dwordx4 v140, s[2:3]
	s_add_i32 m0, s34, 0x16000
	v_mov_b32_e32 v137, v1
	global_load_lds_dwordx4 v136, s[2:3]
	v_readlane_b32 s3, v249, 14
	s_mul_i32 s2, s3, 0x60000
	s_add_u32 s42, s4, s2
	s_mul_hi_i32 s2, s3, 0x60000
	s_addc_u32 s43, s28, s2
	s_add_i32 s71, s34, 0x2000
	s_mov_b32 m0, s34
	s_add_u32 s2, s42, 0x30000
	global_load_lds_dwordx4 v142, s[42:43]
	s_mov_b32 m0, s71
	s_addc_u32 s3, s43, 0
	s_add_i32 s80, s34, 0x4000
	global_load_lds_dwordx4 v138, s[42:43]
	s_mov_b32 m0, s80
	s_add_i32 s81, s34, 0x6000
	global_load_lds_dwordx4 v142, s[2:3]
	s_mov_b32 m0, s81
	v_mov_b32_e32 v143, v1
	global_load_lds_dwordx4 v138, s[2:3]
	v_mov_b32_e32 v139, v1
	s_cmp_eq_u32 s0, 1
	v_lshl_add_u64 v[8:9], s[40:41], 0, v[140:141]
	v_lshl_add_u64 v[6:7], s[40:41], 0, v[136:137]
	v_lshl_add_u64 v[2:3], s[42:43], 0, v[142:143]
	s_cselect_b64 s[2:3], -1, 0
	s_cmp_lg_u32 s0, 1
	v_lshl_add_u64 v[4:5], s[42:43], 0, v[138:139]
	s_cbranch_scc1 .LBB0_342
	s_barrier
.LBB0_342:
	s_add_u32 s6, s10, 0xaa00000
	s_addc_u32 s7, s11, 0
	s_add_u32 s8, s10, 0xca00000
	s_addc_u32 s9, s11, 0
	s_add_u32 s10, s10, 0x10c00000
	s_addc_u32 s11, s11, 0
	s_and_b32 s16, s13, 3
	v_and_b32_e32 v10, 48, v0
	v_lshlrev_b32_e32 v11, 6, v0
	s_movk_i32 s13, 0x3c0
	v_lshlrev_b32_e32 v0, 2, v0
	s_lshl_b32 s82, s0, 6
	s_lshl_b32 s0, s0, 13
	v_and_or_b32 v10, v11, s13, v10
	v_and_b32_e32 v0, 32, v0
	s_add_i32 m0, s34, 0x18000
	v_lshl_add_u64 v[8:9], v[8:9], 0, s[52:53]
	v_bitop3_b32 v11, v10, s0, v0 bitop3:0xde
	s_lshl_b32 s0, s16, 5
	s_lshl_b32 s13, s16, 12
	s_waitcnt vmcnt(2)
	s_barrier
	global_load_lds_dwordx4 v[8:9], off
	v_lshl_add_u64 v[6:7], v[6:7], 0, s[52:53]
	s_add_i32 m0, s34, 0x1a000
	s_add_i32 s83, s34, 0x8000
	s_add_i32 s84, s34, 0xa000
	global_load_lds_dwordx4 v[6:7], off
	v_lshl_add_u64 v[2:3], v[2:3], 0, s[52:53]
	s_mov_b32 m0, s83
	s_add_u32 s14, s40, 0x10080
	global_load_lds_dwordx4 v[2:3], off
	v_lshl_add_u64 v[2:3], v[4:5], 0, s[52:53]
	s_mov_b32 m0, s84
	s_addc_u32 s15, s41, 0
	global_load_lds_dwordx4 v[2:3], off
	s_add_i32 m0, s34, 0x1c000
	v_lshl_add_u64 v[2:3], s[14:15], 0, v[140:141]
	global_load_lds_dwordx4 v[2:3], off
	v_lshl_add_u64 v[2:3], s[14:15], 0, v[136:137]
	s_add_i32 m0, s34, 0x1e000
	s_cmpk_lt_u32 s12, 0x100
	global_load_lds_dwordx4 v[2:3], off
	v_bitop3_b32 v148, v10, s13, v0 bitop3:0xde
	s_waitcnt vmcnt(6)
	s_cselect_b64 s[12:13], -1, 0
	s_cmp_gt_u32 s16, 1
	s_cselect_b64 s[14:15], -1, 0
	s_sub_i32 s0, s0, 64
	s_ashr_i32 s85, s0, 5
	s_lshl_b32 s86, s16, 2
	s_mov_b32 s87, 0
	v_add_u32_e32 v149, 0, v11
	v_readlane_b32 s89, v249, 20
	v_readlane_b32 s90, v249, 14
	v_readlane_b32 s20, v251, 22
	v_readlane_b32 s21, v250, 35
	s_nop 3
	s_cmpk_lt_u32 s20, 0x80
	s_cbranch_scc1 .Lukvb_b1
	s_add_i32 s89, s89, 4
	s_add_u32 s20, s20, 0x100
	s_addc_u32 s21, s21, 0
.Lukvb_b1:
	s_barrier
	s_branch .LBB0_345

.LBB0_345:
	s_add_i32 s87, s87, 1
	s_cmp_lt_u32 s20, 0x100
	s_movk_i32 s17, 0x1ff
	s_cselect_b32 s17, 0x17f, s17
	s_cselect_b32 s0, 1, 2
	s_lshl_b32 s0, s0, 7
	s_mul_i32 s0, s87, s0
	s_add_u32 s18, s0, s20
	s_addc_u32 s19, s21, 0
	s_cmp_gt_u32 s18, s17
	s_cselect_b64 vcc, -1, 0
	s_cmp_le_u32 s18, s17
	s_cselect_b64 s[38:39], -1, 0
	s_cbranch_vccnz .LBB0_351
	s_ashr_i32 s0, s18, 31
	s_lshr_b32 s0, s0, 29
	s_add_i32 s0, s18, s0
	s_and_b32 s16, s0, -8
	s_sub_i32 s18, s18, s16
	s_cmp_gt_i32 s18, -1
	s_mov_b64 s[16:17], -1
	s_cbranch_scc0 .LBB0_348
	s_lshl_b32 s19, s18, 6
	s_mov_b64 s[16:17], 0

.LBB0_357:
	s_lshl_b32 s0, s90, 8
	s_add_i32 s0, s0, s82
	v_and_or_b32 v0, v193, 15, s0
	v_bfe_u32 v130, v193, 4, 2
	s_lshr_b32 s17, s0, 11
	v_and_b32_e32 v131, 0x7ff, v0
	s_mov_b32 vcc_lo, -1
	s_mov_b32 vcc_hi, 0
	v_add_f32_e32 v194, v195, v194
	v_add_f32_e32 v196, v196, v197
	v_add_f32_e32 v198, v199, v198
	v_add_f32_e32 v200, v200, v201
	v_add_f32_e32 v202, v203, v202
	v_add_f32_e32 v204, v204, v205
	v_add_f32_e32 v206, v207, v206
	v_add_f32_e32 v208, v208, v209
	v_add_f32_e32 v194, v194, v196
	v_add_f32_e32 v198, v198, v200
	v_add_f32_e32 v202, v202, v204
	v_add_f32_e32 v206, v206, v208
	v_cndmask_b32_e32 v221, 0, v221, vcc
	v_cndmask_b32_e32 v222, 0, v222, vcc
	v_cndmask_b32_e32 v223, 0, v223, vcc
	v_cndmask_b32_e32 v224, 0, v224, vcc
	v_cndmask_b32_e32 v194, 0, v194, vcc
	v_cndmask_b32_e32 v198, 0, v198, vcc
	v_cndmask_b32_e32 v202, 0, v202, vcc
	v_cndmask_b32_e32 v206, 0, v206, vcc
	ds_swizzle_b32 v195, v221 offset:swizzle(SWAP,16)
	ds_swizzle_b32 v196, v222 offset:swizzle(SWAP,16)
	ds_swizzle_b32 v199, v223 offset:swizzle(SWAP,16)
	ds_swizzle_b32 v200, v224 offset:swizzle(SWAP,16)
	ds_swizzle_b32 v203, v194 offset:swizzle(SWAP,16)
	ds_swizzle_b32 v204, v198 offset:swizzle(SWAP,16)
	ds_swizzle_b32 v207, v202 offset:swizzle(SWAP,16)
	ds_swizzle_b32 v208, v206 offset:swizzle(SWAP,16)
	s_waitcnt lgkmcnt(0)
	v_add_f32_e32 v221, v221, v195
	v_add_f32_e32 v222, v222, v196
	v_add_f32_e32 v223, v223, v199
	v_add_f32_e32 v224, v224, v200
	v_add_f32_e32 v194, v194, v203
	v_add_f32_e32 v198, v198, v204
	v_add_f32_e32 v202, v202, v207
	v_add_f32_e32 v206, v206, v208
	v_mov_b32_e32 v197, v221
	v_mov_b32_e32 v201, v222
	v_mov_b32_e32 v205, v223
	v_mov_b32_e32 v209, v224
	v_mov_b32_e32 v240, v194
	v_mov_b32_e32 v241, v198
	v_mov_b32_e32 v242, v202
	v_mov_b32_e32 v243, v206
	v_permlane32_swap_b32_e32 v221, v197
	v_permlane32_swap_b32_e32 v222, v201
	v_permlane32_swap_b32_e32 v223, v205
	v_permlane32_swap_b32_e32 v224, v209
	v_permlane32_swap_b32_e32 v194, v240
	v_permlane32_swap_b32_e32 v198, v241
	v_permlane32_swap_b32_e32 v202, v242
	v_permlane32_swap_b32_e32 v206, v243
	v_add_f32_e32 v221, v221, v197
	v_add_f32_e32 v222, v222, v201
	v_add_f32_e32 v223, v223, v205
	v_add_f32_e32 v224, v224, v209
	v_add_f32_e32 v194, v194, v240
	v_add_f32_e32 v198, v198, v241
	v_add_f32_e32 v202, v202, v242
	v_add_f32_e32 v206, v206, v243
	v_fmamk_f32 v221, v221, 0x3b800000, v192
	v_fmamk_f32 v222, v222, 0x3b800000, v192
	v_fmamk_f32 v223, v223, 0x3b800000, v192
	v_fmamk_f32 v224, v224, 0x3b800000, v192
	v_fmamk_f32 v194, v194, 0x3b800000, v192
	v_fmamk_f32 v198, v198, 0x3b800000, v192
	v_fmamk_f32 v202, v202, 0x3b800000, v192
	v_fmamk_f32 v206, v206, 0x3b800000, v192
	v_rsq_f32_e32 v221, v221
	v_rsq_f32_e32 v222, v222
	v_rsq_f32_e32 v223, v223
	v_rsq_f32_e32 v224, v224
	v_rsq_f32_e32 v194, v194
	v_rsq_f32_e32 v198, v198
	v_rsq_f32_e32 v202, v202
	v_rsq_f32_e32 v206, v206
	s_cmp_lg_u64 s[14:15], 0
	s_cbranch_scc1 .Lkvb_v
	s_lshl_b32 s38, s17, 7
	s_lshl_b32 s39, s89, 4
	s_add_i32 s38, s38, s39
	s_add_i32 s38, s38, s86
	v_add_u32_e32 v144, s38, v130
	v_lshlrev_b32_e32 v144, 15, v144
	v_lshl_add_u32 v132, v131, 4, v144
	v_add_u32_e32 v133, 0x40000, v132
	v_pk_mul_f32 v[126:127], v[126:127], v[220:221] op_sel:[0,1] op_sel_hi:[1,1]
	v_pk_mul_f32 v[128:129], v[128:129], v[220:221] op_sel:[0,1] op_sel_hi:[1,1]
	v_pk_mul_f32 v[122:123], v[122:123], v[220:221] op_sel:[0,1] op_sel_hi:[1,1]
	v_pk_mul_f32 v[124:125], v[124:125], v[220:221] op_sel:[0,1] op_sel_hi:[1,1]
	v_pk_mul_f32 v[118:119], v[118:119], v[220:221] op_sel:[0,1] op_sel_hi:[1,1]
	v_pk_mul_f32 v[120:121], v[120:121], v[220:221] op_sel:[0,1] op_sel_hi:[1,1]
	v_pk_mul_f32 v[114:115], v[114:115], v[220:221] op_sel:[0,1] op_sel_hi:[1,1]
	v_pk_mul_f32 v[116:117], v[116:117], v[220:221] op_sel:[0,1] op_sel_hi:[1,1]
	v_cvt_pk_bf16_f32 v126, v126, v127
	v_cvt_pk_bf16_f32 v127, v128, v129
	v_cvt_pk_bf16_f32 v128, v122, v123
	v_cvt_pk_bf16_f32 v129, v124, v125
	global_store_dwordx4 v132, v[126:129], s[6:7]
	v_cvt_pk_bf16_f32 v118, v118, v119
	v_cvt_pk_bf16_f32 v119, v120, v121
	v_cvt_pk_bf16_f32 v120, v114, v115
	v_cvt_pk_bf16_f32 v121, v116, v117
	global_store_dwordx4 v133, v[118:121], s[6:7]
	v_pk_mul_f32 v[110:111], v[110:111], v[222:223] op_sel_hi:[1,0]
	v_pk_mul_f32 v[112:113], v[112:113], v[222:223] op_sel_hi:[1,0]
	v_pk_mul_f32 v[106:107], v[106:107], v[222:223] op_sel_hi:[1,0]
	v_pk_mul_f32 v[108:109], v[108:109], v[222:223] op_sel_hi:[1,0]
	v_pk_mul_f32 v[102:103], v[102:103], v[222:223] op_sel_hi:[1,0]
	v_pk_mul_f32 v[104:105], v[104:105], v[222:223] op_sel_hi:[1,0]
	v_pk_mul_f32 v[98:99], v[98:99], v[222:223] op_sel_hi:[1,0]
	v_pk_mul_f32 v[100:101], v[100:101], v[222:223] op_sel_hi:[1,0]
	v_cvt_pk_bf16_f32 v110, v110, v111
	v_cvt_pk_bf16_f32 v111, v112, v113
	v_cvt_pk_bf16_f32 v112, v106, v107
	v_cvt_pk_bf16_f32 v113, v108, v109
	global_store_dwordx4 v132, v[110:113], s[6:7] offset:256
	v_cvt_pk_bf16_f32 v102, v102, v103
	v_cvt_pk_bf16_f32 v103, v104, v105
	v_cvt_pk_bf16_f32 v104, v98, v99
	v_cvt_pk_bf16_f32 v105, v100, v101
	global_store_dwordx4 v133, v[102:105], s[6:7] offset:256
	v_pk_mul_f32 v[94:95], v[94:95], v[222:223] op_sel:[0,1] op_sel_hi:[1,1]
	v_pk_mul_f32 v[96:97], v[96:97], v[222:223] op_sel:[0,1] op_sel_hi:[1,1]
	v_pk_mul_f32 v[90:91], v[90:91], v[222:223] op_sel:[0,1] op_sel_hi:[1,1]
	v_pk_mul_f32 v[92:93], v[92:93], v[222:223] op_sel:[0,1] op_sel_hi:[1,1]
	v_pk_mul_f32 v[86:87], v[86:87], v[222:223] op_sel:[0,1] op_sel_hi:[1,1]
	v_pk_mul_f32 v[88:89], v[88:89], v[222:223] op_sel:[0,1] op_sel_hi:[1,1]
	v_pk_mul_f32 v[82:83], v[82:83], v[222:223] op_sel:[0,1] op_sel_hi:[1,1]
	v_pk_mul_f32 v[84:85], v[84:85], v[222:223] op_sel:[0,1] op_sel_hi:[1,1]
	v_cvt_pk_bf16_f32 v94, v94, v95
	v_cvt_pk_bf16_f32 v95, v96, v97
	v_cvt_pk_bf16_f32 v96, v90, v91
	v_cvt_pk_bf16_f32 v97, v92, v93
	global_store_dwordx4 v132, v[94:97], s[6:7] offset:512
	v_cvt_pk_bf16_f32 v86, v86, v87
	v_cvt_pk_bf16_f32 v87, v88, v89
	v_cvt_pk_bf16_f32 v88, v82, v83
	v_cvt_pk_bf16_f32 v89, v84, v85
	global_store_dwordx4 v133, v[86:89], s[6:7] offset:512
	v_pk_mul_f32 v[78:79], v[78:79], v[224:225] op_sel_hi:[1,0]
	v_pk_mul_f32 v[80:81], v[80:81], v[224:225] op_sel_hi:[1,0]
	v_pk_mul_f32 v[74:75], v[74:75], v[224:225] op_sel_hi:[1,0]
	v_pk_mul_f32 v[76:77], v[76:77], v[224:225] op_sel_hi:[1,0]
	v_pk_mul_f32 v[70:71], v[70:71], v[224:225] op_sel_hi:[1,0]
	v_pk_mul_f32 v[72:73], v[72:73], v[224:225] op_sel_hi:[1,0]
	v_pk_mul_f32 v[66:67], v[66:67], v[224:225] op_sel_hi:[1,0]
	v_pk_mul_f32 v[68:69], v[68:69], v[224:225] op_sel_hi:[1,0]
	v_cvt_pk_bf16_f32 v78, v78, v79
	v_cvt_pk_bf16_f32 v79, v80, v81
	v_cvt_pk_bf16_f32 v80, v74, v75
	v_cvt_pk_bf16_f32 v81, v76, v77
	global_store_dwordx4 v132, v[78:81], s[6:7] offset:768
	v_cvt_pk_bf16_f32 v70, v70, v71
	v_cvt_pk_bf16_f32 v71, v72, v73
	v_cvt_pk_bf16_f32 v72, v66, v67
	v_cvt_pk_bf16_f32 v73, v68, v69
	global_store_dwordx4 v133, v[70:73], s[6:7] offset:768
	v_pk_mul_f32 v[62:63], v[62:63], v[194:195] op_sel_hi:[1,0]
	v_pk_mul_f32 v[64:65], v[64:65], v[194:195] op_sel_hi:[1,0]
	v_pk_mul_f32 v[58:59], v[58:59], v[194:195] op_sel_hi:[1,0]
	v_pk_mul_f32 v[60:61], v[60:61], v[194:195] op_sel_hi:[1,0]
	v_pk_mul_f32 v[54:55], v[54:55], v[194:195] op_sel_hi:[1,0]
	v_pk_mul_f32 v[56:57], v[56:57], v[194:195] op_sel_hi:[1,0]
	v_pk_mul_f32 v[50:51], v[50:51], v[194:195] op_sel_hi:[1,0]
	v_pk_mul_f32 v[52:53], v[52:53], v[194:195] op_sel_hi:[1,0]
	v_cvt_pk_bf16_f32 v62, v62, v63
	v_cvt_pk_bf16_f32 v63, v64, v65
	v_cvt_pk_bf16_f32 v64, v58, v59
	v_cvt_pk_bf16_f32 v65, v60, v61
	global_store_dwordx4 v132, v[62:65], s[6:7] offset:2048
	v_cvt_pk_bf16_f32 v54, v54, v55
	v_cvt_pk_bf16_f32 v55, v56, v57
	v_cvt_pk_bf16_f32 v56, v50, v51
	v_cvt_pk_bf16_f32 v57, v52, v53
	global_store_dwordx4 v133, v[54:57], s[6:7] offset:2048
	v_pk_mul_f32 v[46:47], v[46:47], v[198:199] op_sel_hi:[1,0]
	v_pk_mul_f32 v[48:49], v[48:49], v[198:199] op_sel_hi:[1,0]
	v_pk_mul_f32 v[42:43], v[42:43], v[198:199] op_sel_hi:[1,0]
	v_pk_mul_f32 v[44:45], v[44:45], v[198:199] op_sel_hi:[1,0]
	v_pk_mul_f32 v[38:39], v[38:39], v[198:199] op_sel_hi:[1,0]
	v_pk_mul_f32 v[40:41], v[40:41], v[198:199] op_sel_hi:[1,0]
	v_pk_mul_f32 v[34:35], v[34:35], v[198:199] op_sel_hi:[1,0]
	v_pk_mul_f32 v[36:37], v[36:37], v[198:199] op_sel_hi:[1,0]
	v_cvt_pk_bf16_f32 v46, v46, v47
	v_cvt_pk_bf16_f32 v47, v48, v49
	v_cvt_pk_bf16_f32 v48, v42, v43
	v_cvt_pk_bf16_f32 v49, v44, v45
	global_store_dwordx4 v132, v[46:49], s[6:7] offset:2304
	v_cvt_pk_bf16_f32 v38, v38, v39
	v_cvt_pk_bf16_f32 v39, v40, v41
	v_cvt_pk_bf16_f32 v40, v34, v35
	v_cvt_pk_bf16_f32 v41, v36, v37
	global_store_dwordx4 v133, v[38:41], s[6:7] offset:2304
	v_pk_mul_f32 v[30:31], v[30:31], v[202:203] op_sel_hi:[1,0]
	v_pk_mul_f32 v[32:33], v[32:33], v[202:203] op_sel_hi:[1,0]
	v_pk_mul_f32 v[26:27], v[26:27], v[202:203] op_sel_hi:[1,0]
	v_pk_mul_f32 v[28:29], v[28:29], v[202:203] op_sel_hi:[1,0]
	v_pk_mul_f32 v[22:23], v[22:23], v[202:203] op_sel_hi:[1,0]
	v_pk_mul_f32 v[24:25], v[24:25], v[202:203] op_sel_hi:[1,0]
	v_pk_mul_f32 v[18:19], v[18:19], v[202:203] op_sel_hi:[1,0]
	v_pk_mul_f32 v[20:21], v[20:21], v[202:203] op_sel_hi:[1,0]
	v_cvt_pk_bf16_f32 v30, v30, v31
	v_cvt_pk_bf16_f32 v31, v32, v33
	v_cvt_pk_bf16_f32 v32, v26, v27
	v_cvt_pk_bf16_f32 v33, v28, v29
	global_store_dwordx4 v132, v[30:33], s[6:7] offset:2560
	v_cvt_pk_bf16_f32 v22, v22, v23
	v_cvt_pk_bf16_f32 v23, v24, v25
	v_cvt_pk_bf16_f32 v24, v18, v19
	v_cvt_pk_bf16_f32 v25, v20, v21
	global_store_dwordx4 v133, v[22:25], s[6:7] offset:2560
	v_pk_mul_f32 v[14:15], v[14:15], v[206:207] op_sel_hi:[1,0]
	v_pk_mul_f32 v[16:17], v[16:17], v[206:207] op_sel_hi:[1,0]
	v_pk_mul_f32 v[10:11], v[10:11], v[206:207] op_sel_hi:[1,0]
	v_pk_mul_f32 v[12:13], v[12:13], v[206:207] op_sel_hi:[1,0]
	v_pk_mul_f32 v[6:7], v[6:7], v[206:207] op_sel_hi:[1,0]
	v_pk_mul_f32 v[8:9], v[8:9], v[206:207] op_sel_hi:[1,0]
	v_pk_mul_f32 v[2:3], v[2:3], v[206:207] op_sel_hi:[1,0]
	v_pk_mul_f32 v[4:5], v[4:5], v[206:207] op_sel_hi:[1,0]
	v_cvt_pk_bf16_f32 v14, v14, v15
	v_cvt_pk_bf16_f32 v15, v16, v17
	v_cvt_pk_bf16_f32 v16, v10, v11
	v_cvt_pk_bf16_f32 v17, v12, v13
	global_store_dwordx4 v132, v[14:17], s[6:7] offset:2816
	v_cvt_pk_bf16_f32 v6, v6, v7
	v_cvt_pk_bf16_f32 v7, v8, v9
	v_cvt_pk_bf16_f32 v8, v2, v3
	v_cvt_pk_bf16_f32 v9, v4, v5
	global_store_dwordx4 v133, v[6:9], s[6:7] offset:2816
	s_branch .Lkvb_end
.Lkvb_v:
	s_lshl_b32 s38, s17, 5
	s_lshl_b32 s39, s89, 2
	s_add_i32 s38, s38, s39
	s_add_i32 s38, s38, s85
	s_lshl_b32 s38, s38, 17
	v_lshlrev_b32_e32 v144, 4, v130
	v_lshl_add_u32 v144, v131, 6, v144
	v_add_u32_e32 v132, s38, v144
	v_add_u32_e32 v133, 0x40000, v132
	v_add_u32_e32 v134, 0x2000, v132
	v_add_u32_e32 v135, 0x42000, v132
	v_pk_mul_f32 v[126:127], v[126:127], v[220:221] op_sel:[0,1] op_sel_hi:[1,1]
	v_pk_mul_f32 v[128:129], v[128:129], v[220:221] op_sel:[0,1] op_sel_hi:[1,1]
	v_pk_mul_f32 v[122:123], v[122:123], v[220:221] op_sel:[0,1] op_sel_hi:[1,1]
	v_pk_mul_f32 v[124:125], v[124:125], v[220:221] op_sel:[0,1] op_sel_hi:[1,1]
	v_pk_mul_f32 v[118:119], v[118:119], v[220:221] op_sel:[0,1] op_sel_hi:[1,1]
	v_pk_mul_f32 v[120:121], v[120:121], v[220:221] op_sel:[0,1] op_sel_hi:[1,1]
	v_pk_mul_f32 v[114:115], v[114:115], v[220:221] op_sel:[0,1] op_sel_hi:[1,1]
	v_pk_mul_f32 v[116:117], v[116:117], v[220:221] op_sel:[0,1] op_sel_hi:[1,1]
	v_cvt_pk_bf16_f32 v126, v126, v127
	v_cvt_pk_bf16_f32 v127, v128, v129
	v_cvt_pk_bf16_f32 v128, v122, v123
	v_cvt_pk_bf16_f32 v129, v124, v125
	global_store_dwordx4 v132, v[126:129], s[8:9]
	v_cvt_pk_bf16_f32 v118, v118, v119
	v_cvt_pk_bf16_f32 v119, v120, v121
	v_cvt_pk_bf16_f32 v120, v114, v115
	v_cvt_pk_bf16_f32 v121, v116, v117
	global_store_dwordx4 v133, v[118:121], s[8:9]
	v_pk_mul_f32 v[110:111], v[110:111], v[222:223] op_sel_hi:[1,0]
	v_pk_mul_f32 v[112:113], v[112:113], v[222:223] op_sel_hi:[1,0]
	v_pk_mul_f32 v[106:107], v[106:107], v[222:223] op_sel_hi:[1,0]
	v_pk_mul_f32 v[108:109], v[108:109], v[222:223] op_sel_hi:[1,0]
	v_pk_mul_f32 v[102:103], v[102:103], v[222:223] op_sel_hi:[1,0]
	v_pk_mul_f32 v[104:105], v[104:105], v[222:223] op_sel_hi:[1,0]
	v_pk_mul_f32 v[98:99], v[98:99], v[222:223] op_sel_hi:[1,0]
	v_pk_mul_f32 v[100:101], v[100:101], v[222:223] op_sel_hi:[1,0]
	v_cvt_pk_bf16_f32 v110, v110, v111
	v_cvt_pk_bf16_f32 v111, v112, v113
	v_cvt_pk_bf16_f32 v112, v106, v107
	v_cvt_pk_bf16_f32 v113, v108, v109
	global_store_dwordx4 v132, v[110:113], s[8:9] offset:1024
	v_cvt_pk_bf16_f32 v102, v102, v103
	v_cvt_pk_bf16_f32 v103, v104, v105
	v_cvt_pk_bf16_f32 v104, v98, v99
	v_cvt_pk_bf16_f32 v105, v100, v101
	global_store_dwordx4 v133, v[102:105], s[8:9] offset:1024
	v_pk_mul_f32 v[94:95], v[94:95], v[222:223] op_sel:[0,1] op_sel_hi:[1,1]
	v_pk_mul_f32 v[96:97], v[96:97], v[222:223] op_sel:[0,1] op_sel_hi:[1,1]
	v_pk_mul_f32 v[90:91], v[90:91], v[222:223] op_sel:[0,1] op_sel_hi:[1,1]
	v_pk_mul_f32 v[92:93], v[92:93], v[222:223] op_sel:[0,1] op_sel_hi:[1,1]
	v_pk_mul_f32 v[86:87], v[86:87], v[222:223] op_sel:[0,1] op_sel_hi:[1,1]
	v_pk_mul_f32 v[88:89], v[88:89], v[222:223] op_sel:[0,1] op_sel_hi:[1,1]
	v_pk_mul_f32 v[82:83], v[82:83], v[222:223] op_sel:[0,1] op_sel_hi:[1,1]
	v_pk_mul_f32 v[84:85], v[84:85], v[222:223] op_sel:[0,1] op_sel_hi:[1,1]
	v_cvt_pk_bf16_f32 v94, v94, v95
	v_cvt_pk_bf16_f32 v95, v96, v97
	v_cvt_pk_bf16_f32 v96, v90, v91
	v_cvt_pk_bf16_f32 v97, v92, v93
	global_store_dwordx4 v132, v[94:97], s[8:9] offset:2048
	v_cvt_pk_bf16_f32 v86, v86, v87
	v_cvt_pk_bf16_f32 v87, v88, v89
	v_cvt_pk_bf16_f32 v88, v82, v83
	v_cvt_pk_bf16_f32 v89, v84, v85
	global_store_dwordx4 v133, v[86:89], s[8:9] offset:2048
	v_pk_mul_f32 v[78:79], v[78:79], v[224:225] op_sel_hi:[1,0]
	v_pk_mul_f32 v[80:81], v[80:81], v[224:225] op_sel_hi:[1,0]
	v_pk_mul_f32 v[74:75], v[74:75], v[224:225] op_sel_hi:[1,0]
	v_pk_mul_f32 v[76:77], v[76:77], v[224:225] op_sel_hi:[1,0]
	v_pk_mul_f32 v[70:71], v[70:71], v[224:225] op_sel_hi:[1,0]
	v_pk_mul_f32 v[72:73], v[72:73], v[224:225] op_sel_hi:[1,0]
	v_pk_mul_f32 v[66:67], v[66:67], v[224:225] op_sel_hi:[1,0]
	v_pk_mul_f32 v[68:69], v[68:69], v[224:225] op_sel_hi:[1,0]
	v_cvt_pk_bf16_f32 v78, v78, v79
	v_cvt_pk_bf16_f32 v79, v80, v81
	v_cvt_pk_bf16_f32 v80, v74, v75
	v_cvt_pk_bf16_f32 v81, v76, v77
	global_store_dwordx4 v132, v[78:81], s[8:9] offset:3072
	v_cvt_pk_bf16_f32 v70, v70, v71
	v_cvt_pk_bf16_f32 v71, v72, v73
	v_cvt_pk_bf16_f32 v72, v66, v67
	v_cvt_pk_bf16_f32 v73, v68, v69
	global_store_dwordx4 v133, v[70:73], s[8:9] offset:3072
	v_pk_mul_f32 v[62:63], v[62:63], v[194:195] op_sel_hi:[1,0]
	v_pk_mul_f32 v[64:65], v[64:65], v[194:195] op_sel_hi:[1,0]
	v_pk_mul_f32 v[58:59], v[58:59], v[194:195] op_sel_hi:[1,0]
	v_pk_mul_f32 v[60:61], v[60:61], v[194:195] op_sel_hi:[1,0]
	v_pk_mul_f32 v[54:55], v[54:55], v[194:195] op_sel_hi:[1,0]
	v_pk_mul_f32 v[56:57], v[56:57], v[194:195] op_sel_hi:[1,0]
	v_pk_mul_f32 v[50:51], v[50:51], v[194:195] op_sel_hi:[1,0]
	v_pk_mul_f32 v[52:53], v[52:53], v[194:195] op_sel_hi:[1,0]
	v_cvt_pk_bf16_f32 v62, v62, v63
	v_cvt_pk_bf16_f32 v63, v64, v65
	v_cvt_pk_bf16_f32 v64, v58, v59
	v_cvt_pk_bf16_f32 v65, v60, v61
	global_store_dwordx4 v134, v[62:65], s[8:9]
	v_cvt_pk_bf16_f32 v54, v54, v55
	v_cvt_pk_bf16_f32 v55, v56, v57
	v_cvt_pk_bf16_f32 v56, v50, v51
	v_cvt_pk_bf16_f32 v57, v52, v53
	global_store_dwordx4 v135, v[54:57], s[8:9]
	v_pk_mul_f32 v[46:47], v[46:47], v[198:199] op_sel_hi:[1,0]
	v_pk_mul_f32 v[48:49], v[48:49], v[198:199] op_sel_hi:[1,0]
	v_pk_mul_f32 v[42:43], v[42:43], v[198:199] op_sel_hi:[1,0]
	v_pk_mul_f32 v[44:45], v[44:45], v[198:199] op_sel_hi:[1,0]
	v_pk_mul_f32 v[38:39], v[38:39], v[198:199] op_sel_hi:[1,0]
	v_pk_mul_f32 v[40:41], v[40:41], v[198:199] op_sel_hi:[1,0]
	v_pk_mul_f32 v[34:35], v[34:35], v[198:199] op_sel_hi:[1,0]
	v_pk_mul_f32 v[36:37], v[36:37], v[198:199] op_sel_hi:[1,0]
	v_cvt_pk_bf16_f32 v46, v46, v47
	v_cvt_pk_bf16_f32 v47, v48, v49
	v_cvt_pk_bf16_f32 v48, v42, v43
	v_cvt_pk_bf16_f32 v49, v44, v45
	global_store_dwordx4 v134, v[46:49], s[8:9] offset:1024
	v_cvt_pk_bf16_f32 v38, v38, v39
	v_cvt_pk_bf16_f32 v39, v40, v41
	v_cvt_pk_bf16_f32 v40, v34, v35
	v_cvt_pk_bf16_f32 v41, v36, v37
	global_store_dwordx4 v135, v[38:41], s[8:9] offset:1024
	v_pk_mul_f32 v[30:31], v[30:31], v[202:203] op_sel_hi:[1,0]
	v_pk_mul_f32 v[32:33], v[32:33], v[202:203] op_sel_hi:[1,0]
	v_pk_mul_f32 v[26:27], v[26:27], v[202:203] op_sel_hi:[1,0]
	v_pk_mul_f32 v[28:29], v[28:29], v[202:203] op_sel_hi:[1,0]
	v_pk_mul_f32 v[22:23], v[22:23], v[202:203] op_sel_hi:[1,0]
	v_pk_mul_f32 v[24:25], v[24:25], v[202:203] op_sel_hi:[1,0]
	v_pk_mul_f32 v[18:19], v[18:19], v[202:203] op_sel_hi:[1,0]
	v_pk_mul_f32 v[20:21], v[20:21], v[202:203] op_sel_hi:[1,0]
	v_cvt_pk_bf16_f32 v30, v30, v31
	v_cvt_pk_bf16_f32 v31, v32, v33
	v_cvt_pk_bf16_f32 v32, v26, v27
	v_cvt_pk_bf16_f32 v33, v28, v29
	global_store_dwordx4 v134, v[30:33], s[8:9] offset:2048
	v_cvt_pk_bf16_f32 v22, v22, v23
	v_cvt_pk_bf16_f32 v23, v24, v25
	v_cvt_pk_bf16_f32 v24, v18, v19
	v_cvt_pk_bf16_f32 v25, v20, v21
	global_store_dwordx4 v135, v[22:25], s[8:9] offset:2048
	v_pk_mul_f32 v[14:15], v[14:15], v[206:207] op_sel_hi:[1,0]
	v_pk_mul_f32 v[16:17], v[16:17], v[206:207] op_sel_hi:[1,0]
	v_pk_mul_f32 v[10:11], v[10:11], v[206:207] op_sel_hi:[1,0]
	v_pk_mul_f32 v[12:13], v[12:13], v[206:207] op_sel_hi:[1,0]
	v_pk_mul_f32 v[6:7], v[6:7], v[206:207] op_sel_hi:[1,0]
	v_pk_mul_f32 v[8:9], v[8:9], v[206:207] op_sel_hi:[1,0]
	v_pk_mul_f32 v[2:3], v[2:3], v[206:207] op_sel_hi:[1,0]
	v_pk_mul_f32 v[4:5], v[4:5], v[206:207] op_sel_hi:[1,0]
	v_cvt_pk_bf16_f32 v14, v14, v15
	v_cvt_pk_bf16_f32 v15, v16, v17
	v_cvt_pk_bf16_f32 v16, v10, v11
	v_cvt_pk_bf16_f32 v17, v12, v13
	global_store_dwordx4 v134, v[14:17], s[8:9] offset:3072
	v_cvt_pk_bf16_f32 v6, v6, v7
	v_cvt_pk_bf16_f32 v7, v8, v9
	v_cvt_pk_bf16_f32 v8, v2, v3
	v_cvt_pk_bf16_f32 v9, v4, v5
	global_store_dwordx4 v135, v[6:9], s[8:9] offset:3072

.LBB0_626:
	s_lshl_b32 s0, s29, 8
	s_add_i32 s0, s0, s87
	v_and_or_b32 v0, v193, 15, s0
	v_bfe_u32 v142, v193, 4, 2
	s_lshr_b32 s17, s0, 11
	v_and_b32_e32 v143, 0x7ff, v0
	s_cmp_lt_u32 s28, 4
	s_cselect_b32 s0, 0x3e38aa3b, 1.0
	v_add_f32_e32 v194, v195, v194
	v_add_f32_e32 v196, v196, v197
	v_add_f32_e32 v198, v199, v198
	v_add_f32_e32 v200, v200, v201
	v_add_f32_e32 v202, v203, v202
	v_add_f32_e32 v204, v204, v205
	v_add_f32_e32 v206, v207, v206
	v_add_f32_e32 v208, v208, v209
	v_add_f32_e32 v194, v194, v196
	v_add_f32_e32 v198, v198, v200
	v_add_f32_e32 v202, v202, v204
	v_add_f32_e32 v206, v206, v208
	ds_swizzle_b32 v195, v221 offset:swizzle(SWAP,16)
	ds_swizzle_b32 v196, v222 offset:swizzle(SWAP,16)
	ds_swizzle_b32 v199, v223 offset:swizzle(SWAP,16)
	ds_swizzle_b32 v200, v224 offset:swizzle(SWAP,16)
	ds_swizzle_b32 v203, v194 offset:swizzle(SWAP,16)
	ds_swizzle_b32 v204, v198 offset:swizzle(SWAP,16)
	ds_swizzle_b32 v207, v202 offset:swizzle(SWAP,16)
	ds_swizzle_b32 v208, v206 offset:swizzle(SWAP,16)
	s_waitcnt lgkmcnt(0)
	v_add_f32_e32 v221, v221, v195
	v_add_f32_e32 v222, v222, v196
	v_add_f32_e32 v223, v223, v199
	v_add_f32_e32 v224, v224, v200
	v_add_f32_e32 v194, v194, v203
	v_add_f32_e32 v198, v198, v204
	v_add_f32_e32 v202, v202, v207
	v_add_f32_e32 v206, v206, v208
	v_mov_b32_e32 v197, v221
	v_mov_b32_e32 v201, v222
	v_mov_b32_e32 v205, v223
	v_mov_b32_e32 v209, v224
	v_mov_b32_e32 v240, v194
	v_mov_b32_e32 v241, v198
	v_mov_b32_e32 v242, v202
	v_mov_b32_e32 v243, v206
	v_permlane32_swap_b32_e32 v221, v197
	v_permlane32_swap_b32_e32 v222, v201
	v_permlane32_swap_b32_e32 v223, v205
	v_permlane32_swap_b32_e32 v224, v209
	v_permlane32_swap_b32_e32 v194, v240
	v_permlane32_swap_b32_e32 v198, v241
	v_permlane32_swap_b32_e32 v202, v242
	v_permlane32_swap_b32_e32 v206, v243
	v_add_f32_e32 v221, v221, v197
	v_add_f32_e32 v222, v222, v201
	v_add_f32_e32 v223, v223, v205
	v_add_f32_e32 v224, v224, v209
	v_add_f32_e32 v194, v194, v240
	v_add_f32_e32 v198, v198, v241
	v_add_f32_e32 v202, v202, v242
	v_add_f32_e32 v206, v206, v243
	v_fmamk_f32 v221, v221, 0x3a800000, v192
	v_fmamk_f32 v222, v222, 0x3a800000, v192
	v_fmamk_f32 v223, v223, 0x3a800000, v192
	v_fmamk_f32 v224, v224, 0x3a800000, v192
	v_fmamk_f32 v194, v194, 0x3a800000, v192
	v_fmamk_f32 v198, v198, 0x3a800000, v192
	v_fmamk_f32 v202, v202, 0x3a800000, v192
	v_fmamk_f32 v206, v206, 0x3a800000, v192
	v_rsq_f32_e32 v221, v221
	v_rsq_f32_e32 v222, v222
	v_rsq_f32_e32 v223, v223
	v_rsq_f32_e32 v224, v224
	v_rsq_f32_e32 v194, v194
	v_rsq_f32_e32 v198, v198
	v_rsq_f32_e32 v202, v202
	v_rsq_f32_e32 v206, v206
	v_mul_f32_e32 v221, s0, v221
	v_mul_f32_e32 v222, s0, v222
	v_mul_f32_e32 v223, s0, v223
	v_mul_f32_e32 v224, s0, v224
	v_mul_f32_e32 v194, s0, v194
	v_mul_f32_e32 v198, s0, v198
	v_mul_f32_e32 v202, s0, v202
	v_mul_f32_e32 v206, s0, v206
	s_lshr_b32 s38, s88, 5
	s_cmp_lt_u32 s28, 4
	s_cbranch_scc0 .Lqkv_kv
	s_lshl_b32 s39, s28, 9
	s_lshl_b32 s38, s88, 1
	s_or_b32 s39, s39, s38
	v_lshl_or_b32 v148, v142, 4, s39
	v_mad_u32_u24 v144, v0, s47, v148
	v_pk_mul_f32 v[126:127], v[126:127], v[220:221] op_sel:[0,1] op_sel_hi:[1,1]
	v_pk_mul_f32 v[128:129], v[128:129], v[220:221] op_sel:[0,1] op_sel_hi:[1,1]
	v_pk_mul_f32 v[122:123], v[122:123], v[220:221] op_sel:[0,1] op_sel_hi:[1,1]
	v_pk_mul_f32 v[124:125], v[124:125], v[220:221] op_sel:[0,1] op_sel_hi:[1,1]
	v_pk_mul_f32 v[118:119], v[118:119], v[220:221] op_sel:[0,1] op_sel_hi:[1,1]
	v_pk_mul_f32 v[120:121], v[120:121], v[220:221] op_sel:[0,1] op_sel_hi:[1,1]
	v_pk_mul_f32 v[114:115], v[114:115], v[220:221] op_sel:[0,1] op_sel_hi:[1,1]
	v_pk_mul_f32 v[116:117], v[116:117], v[220:221] op_sel:[0,1] op_sel_hi:[1,1]
	v_cvt_pk_bf16_f32 v126, v126, v127
	v_cvt_pk_bf16_f32 v127, v128, v129
	v_cvt_pk_bf16_f32 v128, v122, v123
	v_cvt_pk_bf16_f32 v129, v124, v125
	v_add_u32_e32 v145, 0x0, v144
	global_store_dwordx4 v145, v[126:129], s[6:7]
	v_cvt_pk_bf16_f32 v118, v118, v119
	v_cvt_pk_bf16_f32 v119, v120, v121
	v_cvt_pk_bf16_f32 v120, v114, v115
	v_cvt_pk_bf16_f32 v121, v116, v117
	v_add_u32_e32 v146, 0x0, v144
	global_store_dwordx4 v146, v[118:121], s[6:7] offset:256
	v_pk_mul_f32 v[110:111], v[110:111], v[222:223] op_sel_hi:[1,0]
	v_pk_mul_f32 v[112:113], v[112:113], v[222:223] op_sel_hi:[1,0]
	v_pk_mul_f32 v[106:107], v[106:107], v[222:223] op_sel_hi:[1,0]
	v_pk_mul_f32 v[108:109], v[108:109], v[222:223] op_sel_hi:[1,0]
	v_pk_mul_f32 v[102:103], v[102:103], v[222:223] op_sel_hi:[1,0]
	v_pk_mul_f32 v[104:105], v[104:105], v[222:223] op_sel_hi:[1,0]
	v_pk_mul_f32 v[98:99], v[98:99], v[222:223] op_sel_hi:[1,0]
	v_pk_mul_f32 v[100:101], v[100:101], v[222:223] op_sel_hi:[1,0]
	v_cvt_pk_bf16_f32 v110, v110, v111
	v_cvt_pk_bf16_f32 v111, v112, v113
	v_cvt_pk_bf16_f32 v112, v106, v107
	v_cvt_pk_bf16_f32 v113, v108, v109
	v_add_u32_e32 v145, 0xc000, v144
	global_store_dwordx4 v145, v[110:113], s[6:7]
	v_cvt_pk_bf16_f32 v102, v102, v103
	v_cvt_pk_bf16_f32 v103, v104, v105
	v_cvt_pk_bf16_f32 v104, v98, v99
	v_cvt_pk_bf16_f32 v105, v100, v101
	v_add_u32_e32 v146, 0xc000, v144
	global_store_dwordx4 v146, v[102:105], s[6:7] offset:256
	v_pk_mul_f32 v[94:95], v[94:95], v[222:223] op_sel:[0,1] op_sel_hi:[1,1]
	v_pk_mul_f32 v[96:97], v[96:97], v[222:223] op_sel:[0,1] op_sel_hi:[1,1]
	v_pk_mul_f32 v[90:91], v[90:91], v[222:223] op_sel:[0,1] op_sel_hi:[1,1]
	v_pk_mul_f32 v[92:93], v[92:93], v[222:223] op_sel:[0,1] op_sel_hi:[1,1]
	v_pk_mul_f32 v[86:87], v[86:87], v[222:223] op_sel:[0,1] op_sel_hi:[1,1]
	v_pk_mul_f32 v[88:89], v[88:89], v[222:223] op_sel:[0,1] op_sel_hi:[1,1]
	v_pk_mul_f32 v[82:83], v[82:83], v[222:223] op_sel:[0,1] op_sel_hi:[1,1]
	v_pk_mul_f32 v[84:85], v[84:85], v[222:223] op_sel:[0,1] op_sel_hi:[1,1]
	v_cvt_pk_bf16_f32 v94, v94, v95
	v_cvt_pk_bf16_f32 v95, v96, v97
	v_cvt_pk_bf16_f32 v96, v90, v91
	v_cvt_pk_bf16_f32 v97, v92, v93
	v_add_u32_e32 v145, 0x18000, v144
	global_store_dwordx4 v145, v[94:97], s[6:7]
	v_cvt_pk_bf16_f32 v86, v86, v87
	v_cvt_pk_bf16_f32 v87, v88, v89
	v_cvt_pk_bf16_f32 v88, v82, v83
	v_cvt_pk_bf16_f32 v89, v84, v85
	v_add_u32_e32 v146, 0x18000, v144
	global_store_dwordx4 v146, v[86:89], s[6:7] offset:256
	v_pk_mul_f32 v[78:79], v[78:79], v[224:225] op_sel_hi:[1,0]
	v_pk_mul_f32 v[80:81], v[80:81], v[224:225] op_sel_hi:[1,0]
	v_pk_mul_f32 v[74:75], v[74:75], v[224:225] op_sel_hi:[1,0]
	v_pk_mul_f32 v[76:77], v[76:77], v[224:225] op_sel_hi:[1,0]
	v_pk_mul_f32 v[70:71], v[70:71], v[224:225] op_sel_hi:[1,0]
	v_pk_mul_f32 v[72:73], v[72:73], v[224:225] op_sel_hi:[1,0]
	v_pk_mul_f32 v[66:67], v[66:67], v[224:225] op_sel_hi:[1,0]
	v_pk_mul_f32 v[68:69], v[68:69], v[224:225] op_sel_hi:[1,0]
	v_cvt_pk_bf16_f32 v78, v78, v79
	v_cvt_pk_bf16_f32 v79, v80, v81
	v_cvt_pk_bf16_f32 v80, v74, v75
	v_cvt_pk_bf16_f32 v81, v76, v77
	v_add_u32_e32 v145, 0x24000, v144
	global_store_dwordx4 v145, v[78:81], s[6:7]
	v_cvt_pk_bf16_f32 v70, v70, v71
	v_cvt_pk_bf16_f32 v71, v72, v73
	v_cvt_pk_bf16_f32 v72, v66, v67
	v_cvt_pk_bf16_f32 v73, v68, v69
	v_add_u32_e32 v146, 0x24000, v144
	global_store_dwordx4 v146, v[70:73], s[6:7] offset:256
	v_pk_mul_f32 v[62:63], v[62:63], v[194:195] op_sel_hi:[1,0]
	v_pk_mul_f32 v[64:65], v[64:65], v[194:195] op_sel_hi:[1,0]
	v_pk_mul_f32 v[58:59], v[58:59], v[194:195] op_sel_hi:[1,0]
	v_pk_mul_f32 v[60:61], v[60:61], v[194:195] op_sel_hi:[1,0]
	v_pk_mul_f32 v[54:55], v[54:55], v[194:195] op_sel_hi:[1,0]
	v_pk_mul_f32 v[56:57], v[56:57], v[194:195] op_sel_hi:[1,0]
	v_pk_mul_f32 v[50:51], v[50:51], v[194:195] op_sel_hi:[1,0]
	v_pk_mul_f32 v[52:53], v[52:53], v[194:195] op_sel_hi:[1,0]
	v_cvt_pk_bf16_f32 v62, v62, v63
	v_cvt_pk_bf16_f32 v63, v64, v65
	v_cvt_pk_bf16_f32 v64, v58, v59
	v_cvt_pk_bf16_f32 v65, v60, v61
	v_add_u32_e32 v145, 0x60000, v144
	global_store_dwordx4 v145, v[62:65], s[6:7]
	v_cvt_pk_bf16_f32 v54, v54, v55
	v_cvt_pk_bf16_f32 v55, v56, v57
	v_cvt_pk_bf16_f32 v56, v50, v51
	v_cvt_pk_bf16_f32 v57, v52, v53
	v_add_u32_e32 v146, 0x60000, v144
	global_store_dwordx4 v146, v[54:57], s[6:7] offset:256
	v_pk_mul_f32 v[46:47], v[46:47], v[198:199] op_sel_hi:[1,0]
	v_pk_mul_f32 v[48:49], v[48:49], v[198:199] op_sel_hi:[1,0]
	v_pk_mul_f32 v[42:43], v[42:43], v[198:199] op_sel_hi:[1,0]
	v_pk_mul_f32 v[44:45], v[44:45], v[198:199] op_sel_hi:[1,0]
	v_pk_mul_f32 v[38:39], v[38:39], v[198:199] op_sel_hi:[1,0]
	v_pk_mul_f32 v[40:41], v[40:41], v[198:199] op_sel_hi:[1,0]
	v_pk_mul_f32 v[34:35], v[34:35], v[198:199] op_sel_hi:[1,0]
	v_pk_mul_f32 v[36:37], v[36:37], v[198:199] op_sel_hi:[1,0]
	v_cvt_pk_bf16_f32 v46, v46, v47
	v_cvt_pk_bf16_f32 v47, v48, v49
	v_cvt_pk_bf16_f32 v48, v42, v43
	v_cvt_pk_bf16_f32 v49, v44, v45
	v_add_u32_e32 v145, 0x6c000, v144
	global_store_dwordx4 v145, v[46:49], s[6:7]
	v_cvt_pk_bf16_f32 v38, v38, v39
	v_cvt_pk_bf16_f32 v39, v40, v41
	v_cvt_pk_bf16_f32 v40, v34, v35
	v_cvt_pk_bf16_f32 v41, v36, v37
	v_add_u32_e32 v146, 0x6c000, v144
	global_store_dwordx4 v146, v[38:41], s[6:7] offset:256
	v_pk_mul_f32 v[30:31], v[30:31], v[202:203] op_sel_hi:[1,0]
	v_pk_mul_f32 v[32:33], v[32:33], v[202:203] op_sel_hi:[1,0]
	v_pk_mul_f32 v[26:27], v[26:27], v[202:203] op_sel_hi:[1,0]
	v_pk_mul_f32 v[28:29], v[28:29], v[202:203] op_sel_hi:[1,0]
	v_pk_mul_f32 v[22:23], v[22:23], v[202:203] op_sel_hi:[1,0]
	v_pk_mul_f32 v[24:25], v[24:25], v[202:203] op_sel_hi:[1,0]
	v_pk_mul_f32 v[18:19], v[18:19], v[202:203] op_sel_hi:[1,0]
	v_pk_mul_f32 v[20:21], v[20:21], v[202:203] op_sel_hi:[1,0]
	v_cvt_pk_bf16_f32 v30, v30, v31
	v_cvt_pk_bf16_f32 v31, v32, v33
	v_cvt_pk_bf16_f32 v32, v26, v27
	v_cvt_pk_bf16_f32 v33, v28, v29
	v_add_u32_e32 v145, 0x78000, v144
	global_store_dwordx4 v145, v[30:33], s[6:7]
	v_cvt_pk_bf16_f32 v22, v22, v23
	v_cvt_pk_bf16_f32 v23, v24, v25
	v_cvt_pk_bf16_f32 v24, v18, v19
	v_cvt_pk_bf16_f32 v25, v20, v21
	v_add_u32_e32 v146, 0x78000, v144
	global_store_dwordx4 v146, v[22:25], s[6:7] offset:256
	v_pk_mul_f32 v[14:15], v[14:15], v[206:207] op_sel_hi:[1,0]
	v_pk_mul_f32 v[16:17], v[16:17], v[206:207] op_sel_hi:[1,0]
	v_pk_mul_f32 v[10:11], v[10:11], v[206:207] op_sel_hi:[1,0]
	v_pk_mul_f32 v[12:13], v[12:13], v[206:207] op_sel_hi:[1,0]
	v_pk_mul_f32 v[6:7], v[6:7], v[206:207] op_sel_hi:[1,0]
	v_pk_mul_f32 v[8:9], v[8:9], v[206:207] op_sel_hi:[1,0]
	v_pk_mul_f32 v[2:3], v[2:3], v[206:207] op_sel_hi:[1,0]
	v_pk_mul_f32 v[4:5], v[4:5], v[206:207] op_sel_hi:[1,0]
	v_cvt_pk_bf16_f32 v14, v14, v15
	v_cvt_pk_bf16_f32 v15, v16, v17
	v_cvt_pk_bf16_f32 v16, v10, v11
	v_cvt_pk_bf16_f32 v17, v12, v13
	v_add_u32_e32 v145, 0x84000, v144
	global_store_dwordx4 v145, v[14:17], s[6:7]
	v_cvt_pk_bf16_f32 v6, v6, v7
	v_cvt_pk_bf16_f32 v7, v8, v9
	v_cvt_pk_bf16_f32 v8, v2, v3
	v_cvt_pk_bf16_f32 v9, v4, v5
	v_add_u32_e32 v146, 0x84000, v144
	global_store_dwordx4 v146, v[6:9], s[6:7] offset:256
	s_branch .Lqkv_end
.Lqkv_kv:
	s_cmp_eq_u32 s28, 4
	s_cbranch_scc0 .Lqkv_v
	s_lshl_b32 s39, s17, 5
	s_lshl_b32 s38, s38, 2
	s_add_i32 s39, s39, s38
	v_add_u32_e32 v148, s39, v142
	v_lshlrev_b32_e32 v148, 15, v148
	v_lshl_add_u32 v144, v143, 4, v148
	v_add_u32_e32 v145, 0x80000, v144
	v_pk_mul_f32 v[126:127], v[126:127], v[220:221] op_sel:[0,1] op_sel_hi:[1,1]
	v_pk_mul_f32 v[128:129], v[128:129], v[220:221] op_sel:[0,1] op_sel_hi:[1,1]
	v_pk_mul_f32 v[122:123], v[122:123], v[220:221] op_sel:[0,1] op_sel_hi:[1,1]
	v_pk_mul_f32 v[124:125], v[124:125], v[220:221] op_sel:[0,1] op_sel_hi:[1,1]
	v_pk_mul_f32 v[118:119], v[118:119], v[220:221] op_sel:[0,1] op_sel_hi:[1,1]
	v_pk_mul_f32 v[120:121], v[120:121], v[220:221] op_sel:[0,1] op_sel_hi:[1,1]
	v_pk_mul_f32 v[114:115], v[114:115], v[220:221] op_sel:[0,1] op_sel_hi:[1,1]
	v_pk_mul_f32 v[116:117], v[116:117], v[220:221] op_sel:[0,1] op_sel_hi:[1,1]
	v_cvt_pk_bf16_f32 v126, v126, v127
	v_cvt_pk_bf16_f32 v127, v128, v129
	v_cvt_pk_bf16_f32 v128, v122, v123
	v_cvt_pk_bf16_f32 v129, v124, v125
	global_store_dwordx4 v144, v[126:129], s[8:9]
	v_cvt_pk_bf16_f32 v118, v118, v119
	v_cvt_pk_bf16_f32 v119, v120, v121
	v_cvt_pk_bf16_f32 v120, v114, v115
	v_cvt_pk_bf16_f32 v121, v116, v117
	global_store_dwordx4 v145, v[118:121], s[8:9]
	v_pk_mul_f32 v[110:111], v[110:111], v[222:223] op_sel_hi:[1,0]
	v_pk_mul_f32 v[112:113], v[112:113], v[222:223] op_sel_hi:[1,0]
	v_pk_mul_f32 v[106:107], v[106:107], v[222:223] op_sel_hi:[1,0]
	v_pk_mul_f32 v[108:109], v[108:109], v[222:223] op_sel_hi:[1,0]
	v_pk_mul_f32 v[102:103], v[102:103], v[222:223] op_sel_hi:[1,0]
	v_pk_mul_f32 v[104:105], v[104:105], v[222:223] op_sel_hi:[1,0]
	v_pk_mul_f32 v[98:99], v[98:99], v[222:223] op_sel_hi:[1,0]
	v_pk_mul_f32 v[100:101], v[100:101], v[222:223] op_sel_hi:[1,0]
	v_cvt_pk_bf16_f32 v110, v110, v111
	v_cvt_pk_bf16_f32 v111, v112, v113
	v_cvt_pk_bf16_f32 v112, v106, v107
	v_cvt_pk_bf16_f32 v113, v108, v109
	global_store_dwordx4 v144, v[110:113], s[8:9] offset:256
	v_cvt_pk_bf16_f32 v102, v102, v103
	v_cvt_pk_bf16_f32 v103, v104, v105
	v_cvt_pk_bf16_f32 v104, v98, v99
	v_cvt_pk_bf16_f32 v105, v100, v101
	global_store_dwordx4 v145, v[102:105], s[8:9] offset:256
	v_pk_mul_f32 v[94:95], v[94:95], v[222:223] op_sel:[0,1] op_sel_hi:[1,1]
	v_pk_mul_f32 v[96:97], v[96:97], v[222:223] op_sel:[0,1] op_sel_hi:[1,1]
	v_pk_mul_f32 v[90:91], v[90:91], v[222:223] op_sel:[0,1] op_sel_hi:[1,1]
	v_pk_mul_f32 v[92:93], v[92:93], v[222:223] op_sel:[0,1] op_sel_hi:[1,1]
	v_pk_mul_f32 v[86:87], v[86:87], v[222:223] op_sel:[0,1] op_sel_hi:[1,1]
	v_pk_mul_f32 v[88:89], v[88:89], v[222:223] op_sel:[0,1] op_sel_hi:[1,1]
	v_pk_mul_f32 v[82:83], v[82:83], v[222:223] op_sel:[0,1] op_sel_hi:[1,1]
	v_pk_mul_f32 v[84:85], v[84:85], v[222:223] op_sel:[0,1] op_sel_hi:[1,1]
	v_cvt_pk_bf16_f32 v94, v94, v95
	v_cvt_pk_bf16_f32 v95, v96, v97
	v_cvt_pk_bf16_f32 v96, v90, v91
	v_cvt_pk_bf16_f32 v97, v92, v93
	global_store_dwordx4 v144, v[94:97], s[8:9] offset:512
	v_cvt_pk_bf16_f32 v86, v86, v87
	v_cvt_pk_bf16_f32 v87, v88, v89
	v_cvt_pk_bf16_f32 v88, v82, v83
	v_cvt_pk_bf16_f32 v89, v84, v85
	global_store_dwordx4 v145, v[86:89], s[8:9] offset:512
	v_pk_mul_f32 v[78:79], v[78:79], v[224:225] op_sel_hi:[1,0]
	v_pk_mul_f32 v[80:81], v[80:81], v[224:225] op_sel_hi:[1,0]
	v_pk_mul_f32 v[74:75], v[74:75], v[224:225] op_sel_hi:[1,0]
	v_pk_mul_f32 v[76:77], v[76:77], v[224:225] op_sel_hi:[1,0]
	v_pk_mul_f32 v[70:71], v[70:71], v[224:225] op_sel_hi:[1,0]
	v_pk_mul_f32 v[72:73], v[72:73], v[224:225] op_sel_hi:[1,0]
	v_pk_mul_f32 v[66:67], v[66:67], v[224:225] op_sel_hi:[1,0]
	v_pk_mul_f32 v[68:69], v[68:69], v[224:225] op_sel_hi:[1,0]
	v_cvt_pk_bf16_f32 v78, v78, v79
	v_cvt_pk_bf16_f32 v79, v80, v81
	v_cvt_pk_bf16_f32 v80, v74, v75
	v_cvt_pk_bf16_f32 v81, v76, v77
	global_store_dwordx4 v144, v[78:81], s[8:9] offset:768
	v_cvt_pk_bf16_f32 v70, v70, v71
	v_cvt_pk_bf16_f32 v71, v72, v73
	v_cvt_pk_bf16_f32 v72, v66, v67
	v_cvt_pk_bf16_f32 v73, v68, v69
	global_store_dwordx4 v145, v[70:73], s[8:9] offset:768
	v_pk_mul_f32 v[62:63], v[62:63], v[194:195] op_sel_hi:[1,0]
	v_pk_mul_f32 v[64:65], v[64:65], v[194:195] op_sel_hi:[1,0]
	v_pk_mul_f32 v[58:59], v[58:59], v[194:195] op_sel_hi:[1,0]
	v_pk_mul_f32 v[60:61], v[60:61], v[194:195] op_sel_hi:[1,0]
	v_pk_mul_f32 v[54:55], v[54:55], v[194:195] op_sel_hi:[1,0]
	v_pk_mul_f32 v[56:57], v[56:57], v[194:195] op_sel_hi:[1,0]
	v_pk_mul_f32 v[50:51], v[50:51], v[194:195] op_sel_hi:[1,0]
	v_pk_mul_f32 v[52:53], v[52:53], v[194:195] op_sel_hi:[1,0]
	v_cvt_pk_bf16_f32 v62, v62, v63
	v_cvt_pk_bf16_f32 v63, v64, v65
	v_cvt_pk_bf16_f32 v64, v58, v59
	v_cvt_pk_bf16_f32 v65, v60, v61
	global_store_dwordx4 v144, v[62:65], s[8:9] offset:2048
	v_cvt_pk_bf16_f32 v54, v54, v55
	v_cvt_pk_bf16_f32 v55, v56, v57
	v_cvt_pk_bf16_f32 v56, v50, v51
	v_cvt_pk_bf16_f32 v57, v52, v53
	global_store_dwordx4 v145, v[54:57], s[8:9] offset:2048
	v_pk_mul_f32 v[46:47], v[46:47], v[198:199] op_sel_hi:[1,0]
	v_pk_mul_f32 v[48:49], v[48:49], v[198:199] op_sel_hi:[1,0]
	v_pk_mul_f32 v[42:43], v[42:43], v[198:199] op_sel_hi:[1,0]
	v_pk_mul_f32 v[44:45], v[44:45], v[198:199] op_sel_hi:[1,0]
	v_pk_mul_f32 v[38:39], v[38:39], v[198:199] op_sel_hi:[1,0]
	v_pk_mul_f32 v[40:41], v[40:41], v[198:199] op_sel_hi:[1,0]
	v_pk_mul_f32 v[34:35], v[34:35], v[198:199] op_sel_hi:[1,0]
	v_pk_mul_f32 v[36:37], v[36:37], v[198:199] op_sel_hi:[1,0]
	v_cvt_pk_bf16_f32 v46, v46, v47
	v_cvt_pk_bf16_f32 v47, v48, v49
	v_cvt_pk_bf16_f32 v48, v42, v43
	v_cvt_pk_bf16_f32 v49, v44, v45
	global_store_dwordx4 v144, v[46:49], s[8:9] offset:2304
	v_cvt_pk_bf16_f32 v38, v38, v39
	v_cvt_pk_bf16_f32 v39, v40, v41
	v_cvt_pk_bf16_f32 v40, v34, v35
	v_cvt_pk_bf16_f32 v41, v36, v37
	global_store_dwordx4 v145, v[38:41], s[8:9] offset:2304
	v_pk_mul_f32 v[30:31], v[30:31], v[202:203] op_sel_hi:[1,0]
	v_pk_mul_f32 v[32:33], v[32:33], v[202:203] op_sel_hi:[1,0]
	v_pk_mul_f32 v[26:27], v[26:27], v[202:203] op_sel_hi:[1,0]
	v_pk_mul_f32 v[28:29], v[28:29], v[202:203] op_sel_hi:[1,0]
	v_pk_mul_f32 v[22:23], v[22:23], v[202:203] op_sel_hi:[1,0]
	v_pk_mul_f32 v[24:25], v[24:25], v[202:203] op_sel_hi:[1,0]
	v_pk_mul_f32 v[18:19], v[18:19], v[202:203] op_sel_hi:[1,0]
	v_pk_mul_f32 v[20:21], v[20:21], v[202:203] op_sel_hi:[1,0]
	v_cvt_pk_bf16_f32 v30, v30, v31
	v_cvt_pk_bf16_f32 v31, v32, v33
	v_cvt_pk_bf16_f32 v32, v26, v27
	v_cvt_pk_bf16_f32 v33, v28, v29
	global_store_dwordx4 v144, v[30:33], s[8:9] offset:2560
	v_cvt_pk_bf16_f32 v22, v22, v23
	v_cvt_pk_bf16_f32 v23, v24, v25
	v_cvt_pk_bf16_f32 v24, v18, v19
	v_cvt_pk_bf16_f32 v25, v20, v21
	global_store_dwordx4 v145, v[22:25], s[8:9] offset:2560
	v_pk_mul_f32 v[14:15], v[14:15], v[206:207] op_sel_hi:[1,0]
	v_pk_mul_f32 v[16:17], v[16:17], v[206:207] op_sel_hi:[1,0]
	v_pk_mul_f32 v[10:11], v[10:11], v[206:207] op_sel_hi:[1,0]
	v_pk_mul_f32 v[12:13], v[12:13], v[206:207] op_sel_hi:[1,0]
	v_pk_mul_f32 v[6:7], v[6:7], v[206:207] op_sel_hi:[1,0]
	v_pk_mul_f32 v[8:9], v[8:9], v[206:207] op_sel_hi:[1,0]
	v_pk_mul_f32 v[2:3], v[2:3], v[206:207] op_sel_hi:[1,0]
	v_pk_mul_f32 v[4:5], v[4:5], v[206:207] op_sel_hi:[1,0]
	v_cvt_pk_bf16_f32 v14, v14, v15
	v_cvt_pk_bf16_f32 v15, v16, v17
	v_cvt_pk_bf16_f32 v16, v10, v11
	v_cvt_pk_bf16_f32 v17, v12, v13
	global_store_dwordx4 v144, v[14:17], s[8:9] offset:2816
	v_cvt_pk_bf16_f32 v6, v6, v7
	v_cvt_pk_bf16_f32 v7, v8, v9
	v_cvt_pk_bf16_f32 v8, v2, v3
	v_cvt_pk_bf16_f32 v9, v4, v5
	global_store_dwordx4 v145, v[6:9], s[8:9] offset:2816
	s_branch .Lqkv_end
.Lqkv_v:
	s_lshl_b32 s39, s17, 3
	s_add_i32 s39, s39, s38
	s_lshl_b32 s39, s39, 17
	v_lshlrev_b32_e32 v148, 4, v142
	v_lshl_add_u32 v148, v143, 6, v148
	v_add_u32_e32 v144, s39, v148
	v_add_u32_e32 v145, 0x80000, v144
	v_add_u32_e32 v146, 0x2000, v144
	v_add_u32_e32 v147, 0x82000, v144
	v_pk_mul_f32 v[126:127], v[126:127], v[220:221] op_sel:[0,1] op_sel_hi:[1,1]
	v_pk_mul_f32 v[128:129], v[128:129], v[220:221] op_sel:[0,1] op_sel_hi:[1,1]
	v_pk_mul_f32 v[122:123], v[122:123], v[220:221] op_sel:[0,1] op_sel_hi:[1,1]
	v_pk_mul_f32 v[124:125], v[124:125], v[220:221] op_sel:[0,1] op_sel_hi:[1,1]
	v_pk_mul_f32 v[118:119], v[118:119], v[220:221] op_sel:[0,1] op_sel_hi:[1,1]
	v_pk_mul_f32 v[120:121], v[120:121], v[220:221] op_sel:[0,1] op_sel_hi:[1,1]
	v_pk_mul_f32 v[114:115], v[114:115], v[220:221] op_sel:[0,1] op_sel_hi:[1,1]
	v_pk_mul_f32 v[116:117], v[116:117], v[220:221] op_sel:[0,1] op_sel_hi:[1,1]
	v_cvt_pk_bf16_f32 v126, v126, v127
	v_cvt_pk_bf16_f32 v127, v128, v129
	v_cvt_pk_bf16_f32 v128, v122, v123
	v_cvt_pk_bf16_f32 v129, v124, v125
	global_store_dwordx4 v144, v[126:129], s[10:11]
	v_cvt_pk_bf16_f32 v118, v118, v119
	v_cvt_pk_bf16_f32 v119, v120, v121
	v_cvt_pk_bf16_f32 v120, v114, v115
	v_cvt_pk_bf16_f32 v121, v116, v117
	global_store_dwordx4 v145, v[118:121], s[10:11]
	v_pk_mul_f32 v[110:111], v[110:111], v[222:223] op_sel_hi:[1,0]
	v_pk_mul_f32 v[112:113], v[112:113], v[222:223] op_sel_hi:[1,0]
	v_pk_mul_f32 v[106:107], v[106:107], v[222:223] op_sel_hi:[1,0]
	v_pk_mul_f32 v[108:109], v[108:109], v[222:223] op_sel_hi:[1,0]
	v_pk_mul_f32 v[102:103], v[102:103], v[222:223] op_sel_hi:[1,0]
	v_pk_mul_f32 v[104:105], v[104:105], v[222:223] op_sel_hi:[1,0]
	v_pk_mul_f32 v[98:99], v[98:99], v[222:223] op_sel_hi:[1,0]
	v_pk_mul_f32 v[100:101], v[100:101], v[222:223] op_sel_hi:[1,0]
	v_cvt_pk_bf16_f32 v110, v110, v111
	v_cvt_pk_bf16_f32 v111, v112, v113
	v_cvt_pk_bf16_f32 v112, v106, v107
	v_cvt_pk_bf16_f32 v113, v108, v109
	global_store_dwordx4 v144, v[110:113], s[10:11] offset:1024
	v_cvt_pk_bf16_f32 v102, v102, v103
	v_cvt_pk_bf16_f32 v103, v104, v105
	v_cvt_pk_bf16_f32 v104, v98, v99
	v_cvt_pk_bf16_f32 v105, v100, v101
	global_store_dwordx4 v145, v[102:105], s[10:11] offset:1024
	v_pk_mul_f32 v[94:95], v[94:95], v[222:223] op_sel:[0,1] op_sel_hi:[1,1]
	v_pk_mul_f32 v[96:97], v[96:97], v[222:223] op_sel:[0,1] op_sel_hi:[1,1]
	v_pk_mul_f32 v[90:91], v[90:91], v[222:223] op_sel:[0,1] op_sel_hi:[1,1]
	v_pk_mul_f32 v[92:93], v[92:93], v[222:223] op_sel:[0,1] op_sel_hi:[1,1]
	v_pk_mul_f32 v[86:87], v[86:87], v[222:223] op_sel:[0,1] op_sel_hi:[1,1]
	v_pk_mul_f32 v[88:89], v[88:89], v[222:223] op_sel:[0,1] op_sel_hi:[1,1]
	v_pk_mul_f32 v[82:83], v[82:83], v[222:223] op_sel:[0,1] op_sel_hi:[1,1]
	v_pk_mul_f32 v[84:85], v[84:85], v[222:223] op_sel:[0,1] op_sel_hi:[1,1]
	v_cvt_pk_bf16_f32 v94, v94, v95
	v_cvt_pk_bf16_f32 v95, v96, v97
	v_cvt_pk_bf16_f32 v96, v90, v91
	v_cvt_pk_bf16_f32 v97, v92, v93
	global_store_dwordx4 v144, v[94:97], s[10:11] offset:2048
	v_cvt_pk_bf16_f32 v86, v86, v87
	v_cvt_pk_bf16_f32 v87, v88, v89
	v_cvt_pk_bf16_f32 v88, v82, v83
	v_cvt_pk_bf16_f32 v89, v84, v85
	global_store_dwordx4 v145, v[86:89], s[10:11] offset:2048
	v_pk_mul_f32 v[78:79], v[78:79], v[224:225] op_sel_hi:[1,0]
	v_pk_mul_f32 v[80:81], v[80:81], v[224:225] op_sel_hi:[1,0]
	v_pk_mul_f32 v[74:75], v[74:75], v[224:225] op_sel_hi:[1,0]
	v_pk_mul_f32 v[76:77], v[76:77], v[224:225] op_sel_hi:[1,0]
	v_pk_mul_f32 v[70:71], v[70:71], v[224:225] op_sel_hi:[1,0]
	v_pk_mul_f32 v[72:73], v[72:73], v[224:225] op_sel_hi:[1,0]
	v_pk_mul_f32 v[66:67], v[66:67], v[224:225] op_sel_hi:[1,0]
	v_pk_mul_f32 v[68:69], v[68:69], v[224:225] op_sel_hi:[1,0]
	v_cvt_pk_bf16_f32 v78, v78, v79
	v_cvt_pk_bf16_f32 v79, v80, v81
	v_cvt_pk_bf16_f32 v80, v74, v75
	v_cvt_pk_bf16_f32 v81, v76, v77
	global_store_dwordx4 v144, v[78:81], s[10:11] offset:3072
	v_cvt_pk_bf16_f32 v70, v70, v71
	v_cvt_pk_bf16_f32 v71, v72, v73
	v_cvt_pk_bf16_f32 v72, v66, v67
	v_cvt_pk_bf16_f32 v73, v68, v69
	global_store_dwordx4 v145, v[70:73], s[10:11] offset:3072
	v_pk_mul_f32 v[62:63], v[62:63], v[194:195] op_sel_hi:[1,0]
	v_pk_mul_f32 v[64:65], v[64:65], v[194:195] op_sel_hi:[1,0]
	v_pk_mul_f32 v[58:59], v[58:59], v[194:195] op_sel_hi:[1,0]
	v_pk_mul_f32 v[60:61], v[60:61], v[194:195] op_sel_hi:[1,0]
	v_pk_mul_f32 v[54:55], v[54:55], v[194:195] op_sel_hi:[1,0]
	v_pk_mul_f32 v[56:57], v[56:57], v[194:195] op_sel_hi:[1,0]
	v_pk_mul_f32 v[50:51], v[50:51], v[194:195] op_sel_hi:[1,0]
	v_pk_mul_f32 v[52:53], v[52:53], v[194:195] op_sel_hi:[1,0]
	v_cvt_pk_bf16_f32 v62, v62, v63
	v_cvt_pk_bf16_f32 v63, v64, v65
	v_cvt_pk_bf16_f32 v64, v58, v59
	v_cvt_pk_bf16_f32 v65, v60, v61
	global_store_dwordx4 v146, v[62:65], s[10:11]
	v_cvt_pk_bf16_f32 v54, v54, v55
	v_cvt_pk_bf16_f32 v55, v56, v57
	v_cvt_pk_bf16_f32 v56, v50, v51
	v_cvt_pk_bf16_f32 v57, v52, v53
	global_store_dwordx4 v147, v[54:57], s[10:11]
	v_pk_mul_f32 v[46:47], v[46:47], v[198:199] op_sel_hi:[1,0]
	v_pk_mul_f32 v[48:49], v[48:49], v[198:199] op_sel_hi:[1,0]
	v_pk_mul_f32 v[42:43], v[42:43], v[198:199] op_sel_hi:[1,0]
	v_pk_mul_f32 v[44:45], v[44:45], v[198:199] op_sel_hi:[1,0]
	v_pk_mul_f32 v[38:39], v[38:39], v[198:199] op_sel_hi:[1,0]
	v_pk_mul_f32 v[40:41], v[40:41], v[198:199] op_sel_hi:[1,0]
	v_pk_mul_f32 v[34:35], v[34:35], v[198:199] op_sel_hi:[1,0]
	v_pk_mul_f32 v[36:37], v[36:37], v[198:199] op_sel_hi:[1,0]
	v_cvt_pk_bf16_f32 v46, v46, v47
	v_cvt_pk_bf16_f32 v47, v48, v49
	v_cvt_pk_bf16_f32 v48, v42, v43
	v_cvt_pk_bf16_f32 v49, v44, v45
	global_store_dwordx4 v146, v[46:49], s[10:11] offset:1024
	v_cvt_pk_bf16_f32 v38, v38, v39
	v_cvt_pk_bf16_f32 v39, v40, v41
	v_cvt_pk_bf16_f32 v40, v34, v35
	v_cvt_pk_bf16_f32 v41, v36, v37
	global_store_dwordx4 v147, v[38:41], s[10:11] offset:1024
	v_pk_mul_f32 v[30:31], v[30:31], v[202:203] op_sel_hi:[1,0]
	v_pk_mul_f32 v[32:33], v[32:33], v[202:203] op_sel_hi:[1,0]
	v_pk_mul_f32 v[26:27], v[26:27], v[202:203] op_sel_hi:[1,0]
	v_pk_mul_f32 v[28:29], v[28:29], v[202:203] op_sel_hi:[1,0]
	v_pk_mul_f32 v[22:23], v[22:23], v[202:203] op_sel_hi:[1,0]
	v_pk_mul_f32 v[24:25], v[24:25], v[202:203] op_sel_hi:[1,0]
	v_pk_mul_f32 v[18:19], v[18:19], v[202:203] op_sel_hi:[1,0]
	v_pk_mul_f32 v[20:21], v[20:21], v[202:203] op_sel_hi:[1,0]
	v_cvt_pk_bf16_f32 v30, v30, v31
	v_cvt_pk_bf16_f32 v31, v32, v33
	v_cvt_pk_bf16_f32 v32, v26, v27
	v_cvt_pk_bf16_f32 v33, v28, v29
	global_store_dwordx4 v146, v[30:33], s[10:11] offset:2048
	v_cvt_pk_bf16_f32 v22, v22, v23
	v_cvt_pk_bf16_f32 v23, v24, v25
	v_cvt_pk_bf16_f32 v24, v18, v19
	v_cvt_pk_bf16_f32 v25, v20, v21
	global_store_dwordx4 v147, v[22:25], s[10:11] offset:2048
	v_pk_mul_f32 v[14:15], v[14:15], v[206:207] op_sel_hi:[1,0]
	v_pk_mul_f32 v[16:17], v[16:17], v[206:207] op_sel_hi:[1,0]
	v_pk_mul_f32 v[10:11], v[10:11], v[206:207] op_sel_hi:[1,0]
	v_pk_mul_f32 v[12:13], v[12:13], v[206:207] op_sel_hi:[1,0]
	v_pk_mul_f32 v[6:7], v[6:7], v[206:207] op_sel_hi:[1,0]
	v_pk_mul_f32 v[8:9], v[8:9], v[206:207] op_sel_hi:[1,0]
	v_pk_mul_f32 v[2:3], v[2:3], v[206:207] op_sel_hi:[1,0]
	v_pk_mul_f32 v[4:5], v[4:5], v[206:207] op_sel_hi:[1,0]
	v_cvt_pk_bf16_f32 v14, v14, v15
	v_cvt_pk_bf16_f32 v15, v16, v17
	v_cvt_pk_bf16_f32 v16, v10, v11
	v_cvt_pk_bf16_f32 v17, v12, v13
	global_store_dwordx4 v146, v[14:17], s[10:11] offset:3072
	v_cvt_pk_bf16_f32 v6, v6, v7
	v_cvt_pk_bf16_f32 v7, v8, v9
	v_cvt_pk_bf16_f32 v8, v2, v3
	v_cvt_pk_bf16_f32 v9, v4, v5
	global_store_dwordx4 v147, v[6:9], s[10:11] offset:3072
